# A/B at identical placement: the mid-block s_setprio 0 / s_setprio 1 pair in each GEMM MFMA block replaced by two s_nop (priority stays raised through the whole 32-MFMA block)
# speedup vs baseline: 1.0093x; 1.0093x over previous
; #define PG8_STAGE(bufoff, gbase, voff) do { _Pragma("unroll") for (int _i = 0; _i < 2; ++_i) \
;         __builtin_amdgcn_global_load_lds((const unsigned*)((const char*)(gbase) + (voff)[_i]), (LAS unsigned*)(lds + (bufoff) + ldsw + _i * 8192), 16, 0, 0); } while (0)
; #define PG8_LDA(dst, b, h) do { _Pragma("unroll") for (int m = 0; m < 4; ++m) _Pragma("unroll") for (int k = 0; k < 2; ++k) dst[m][k] = *(const LAS bf16x8*)(lds + PG8_SA(b, h) + aoff + m * 2048 + k * 1024); } while (0)
; #define PG8_LDB(dst, b, h) do { _Pragma("unroll") for (int n = 0; n < 2; ++n) _Pragma("unroll") for (int k = 0; k < 2; ++k) dst[n][k] = *(const LAS bf16x8*)(lds + PG8_SB(b, h) + boff + n * 2048 + k * 1024); } while (0)
; #define PG8_MMA(ai, bj, At, Bt) do { __builtin_amdgcn_s_setprio(1); _Pragma("unroll") for (int m = 0; m < 4; ++m) _Pragma("unroll") for (int n = 0; n < 2; ++n) _Pragma("unroll") for (int k = 0; k < 2; ++k) \
;         acc[ai][bj][m][n] = __builtin_amdgcn_mfma_f32_16x16x32_bf16(Bt[n][k], At[m][k], acc[ai][bj][m][n], 0, 0, 0); __builtin_amdgcn_s_setprio(0); } while (0)
; #define PG8_WAIT_V(n) asm volatile("s_waitcnt vmcnt(" #n ")" ::: "memory")
; #define PG8_WAIT_L(n) asm volatile("s_waitcnt lgkmcnt(" #n ")" ::: "memory")
; #define PG8_BAR __builtin_amdgcn_s_barrier()
; #define PG8_SCHED __builtin_amdgcn_sched_barrier(0)
; template <class Epi, class Sched>
; __device__ __forceinline__ void gemm_phase(LAS unsigned char* lds, const Gemm g, const Sched& S, const Epi& E, const int wave_s) {
;     ...
;             PG8_LDB(B0, 0, 0); PG8_LDB(B1, 0, 1); PG8_SCHED; PG8_LDA(At, 0, 0); PG8_STAGE(PG8_SA(1, 1), a1 + hstepA, voffA);
;             PG8_WAIT_V(8); PG8_WAIT_L(0); PG8_BAR; PG8_MMA(0, 0, At, B0); PG8_MMA(0, 1, At, B1); PG8_BAR; PG8_SCHED;
;             PG8_LDA(At, 0, 1); PG8_STAGE(PG8_SB(0, 0), b2, voffB); PG8_STAGE(PG8_SB(0, 1), b2 + hstepB, voffB); PG8_STAGE(PG8_SA(0, 0), a2, voffA);
;             PG8_WAIT_V(8); PG8_WAIT_L(0); PG8_BAR; PG8_MMA(1, 0, At, B0); PG8_MMA(1, 1, At, B1); PG8_BAR; PG8_SCHED;
.LBB0_125:
	ds_read_b128 v[152:155], v149
	ds_read_b128 v[156:159], v149 offset:1024
	ds_read_b128 v[160:163], v149 offset:2048
	ds_read_b128 v[164:167], v149 offset:3072
	ds_read_b128 v[168:171], v150
	ds_read_b128 v[172:175], v150 offset:1024
	ds_read_b128 v[176:179], v150 offset:2048
	ds_read_b128 v[180:183], v150 offset:3072
	s_add_u32 s4, s44, 0xfffc0080
	s_addc_u32 s5, s45, -1
	s_cmp_eq_u32 s65, 12
	s_cselect_b32 s47, s29, s5
	s_cselect_b32 s46, s61, s4
	s_cselect_b32 s5, s27, s64
	s_cselect_b32 s4, s62, s63
	v_lshl_add_u64 v[144:145], s[44:45], 0, v[136:137]
	s_add_i32 m0, s33, 0xc000
	ds_read_b128 v[184:187], v151
	ds_read_b128 v[188:191], v151 offset:1024
	ds_read_b128 v[192:195], v151 offset:2048
	ds_read_b128 v[196:199], v151 offset:3072
	ds_read_b128 v[200:203], v151 offset:4096
	ds_read_b128 v[204:207], v151 offset:5120
	ds_read_b128 v[210:213], v151 offset:6144
	ds_read_b128 v[214:217], v151 offset:7168
	global_load_lds_dwordx4 v[144:145], off
	v_lshl_add_u64 v[144:145], s[44:45], 0, v[138:139]
	s_add_i32 m0, s33, 0xe000
	s_nop 0
	global_load_lds_dwordx4 v[144:145], off
	s_waitcnt vmcnt(8) lgkmcnt(0)
	s_barrier
	s_setprio 1
	v_mfma_f32_16x16x32_bf16 v[124:127], v[152:155], v[184:187], v[124:127]
	v_mfma_f32_16x16x32_bf16 v[120:123], v[160:163], v[184:187], v[120:123]
	v_mfma_f32_16x16x32_bf16 v[116:119], v[152:155], v[192:195], v[116:119]
	v_mfma_f32_16x16x32_bf16 v[108:111], v[160:163], v[192:195], v[108:111]
	v_mfma_f32_16x16x32_bf16 v[100:103], v[152:155], v[200:203], v[100:103]
	v_mfma_f32_16x16x32_bf16 v[92:95], v[160:163], v[200:203], v[92:95]
	v_mfma_f32_16x16x32_bf16 v[84:87], v[152:155], v[210:213], v[84:87]
	v_mfma_f32_16x16x32_bf16 v[76:79], v[160:163], v[210:213], v[76:79]
	v_mfma_f32_16x16x32_bf16 v[124:127], v[156:159], v[188:191], v[124:127]
	v_mfma_f32_16x16x32_bf16 v[120:123], v[164:167], v[188:191], v[120:123]
	v_mfma_f32_16x16x32_bf16 v[116:119], v[156:159], v[196:199], v[116:119]
	v_mfma_f32_16x16x32_bf16 v[108:111], v[164:167], v[196:199], v[108:111]
	v_mfma_f32_16x16x32_bf16 v[100:103], v[156:159], v[204:207], v[100:103]
	v_mfma_f32_16x16x32_bf16 v[92:95], v[164:167], v[204:207], v[92:95]
	v_mfma_f32_16x16x32_bf16 v[84:87], v[156:159], v[214:217], v[84:87]
	v_mfma_f32_16x16x32_bf16 v[76:79], v[164:167], v[214:217], v[76:79]
	s_nop 0
	s_nop 0
	v_mfma_f32_16x16x32_bf16 v[112:115], v[168:171], v[184:187], v[112:115]
	v_mfma_f32_16x16x32_bf16 v[104:107], v[176:179], v[184:187], v[104:107]
	v_mfma_f32_16x16x32_bf16 v[96:99], v[168:171], v[192:195], v[96:99]
	v_mfma_f32_16x16x32_bf16 v[88:91], v[176:179], v[192:195], v[88:91]
	v_mfma_f32_16x16x32_bf16 v[80:83], v[168:171], v[200:203], v[80:83]
	v_mfma_f32_16x16x32_bf16 v[72:75], v[176:179], v[200:203], v[72:75]
	v_mfma_f32_16x16x32_bf16 v[68:71], v[168:171], v[210:213], v[68:71]
	v_mfma_f32_16x16x32_bf16 v[64:67], v[176:179], v[210:213], v[64:67]
	v_mfma_f32_16x16x32_bf16 v[112:115], v[172:175], v[188:191], v[112:115]
	v_mfma_f32_16x16x32_bf16 v[104:107], v[180:183], v[188:191], v[104:107]
	v_mfma_f32_16x16x32_bf16 v[96:99], v[172:175], v[196:199], v[96:99]
	v_mfma_f32_16x16x32_bf16 v[88:91], v[180:183], v[196:199], v[88:91]
	v_mfma_f32_16x16x32_bf16 v[80:83], v[172:175], v[204:207], v[80:83]
	v_mfma_f32_16x16x32_bf16 v[72:75], v[180:183], v[204:207], v[72:75]
	v_mfma_f32_16x16x32_bf16 v[68:71], v[172:175], v[214:217], v[68:71]
	v_mfma_f32_16x16x32_bf16 v[64:67], v[180:183], v[214:217], v[64:67]
	s_setprio 0
	s_barrier
	s_add_i32 s66, s53, s81
	v_lshl_add_u64 v[144:145], s[4:5], 0, v[130:131]
	s_mov_b32 m0, s66
	ds_read_b128 v[184:187], v151 offset:16384
	ds_read_b128 v[188:191], v151 offset:17408
	ds_read_b128 v[192:195], v151 offset:18432
	ds_read_b128 v[196:199], v151 offset:19456
	ds_read_b128 v[200:203], v151 offset:20480
	ds_read_b128 v[204:207], v151 offset:21504
	ds_read_b128 v[210:213], v151 offset:22528
	ds_read_b128 v[214:217], v151 offset:23552
	global_load_lds_dwordx4 v[144:145], off
	s_add_i32 m0, s66, 0x2000
	s_add_u32 s66, s4, 0x40000
	v_lshl_add_u64 v[218:219], s[4:5], 0, v[134:135]
	s_addc_u32 s67, s5, 0
	s_add_i32 s68, s54, s81
	global_load_lds_dwordx4 v[218:219], off
	v_lshl_add_u64 v[220:221], s[66:67], 0, v[130:131]
	s_mov_b32 m0, s68
	v_lshl_add_u64 v[222:223], s[46:47], 0, v[132:133]
	global_load_lds_dwordx4 v[220:221], off
	v_lshl_add_u64 v[220:221], s[66:67], 0, v[134:135]
	s_add_i32 m0, s68, 0x2000
	s_nop 0
	global_load_lds_dwordx4 v[220:221], off
	v_lshl_add_u64 v[220:221], s[46:47], 0, v[128:129]
	s_mov_b32 m0, s33
	s_nop 0
	global_load_lds_dwordx4 v[220:221], off
	s_mov_b32 m0, s35
	s_nop 0
	global_load_lds_dwordx4 v[222:223], off
	s_waitcnt vmcnt(8) lgkmcnt(0)
	s_barrier
; #define PG8_STAGE(bufoff, gbase, voff) do { _Pragma("unroll") for (int _i = 0; _i < 2; ++_i) \
;         __builtin_amdgcn_global_load_lds((const unsigned*)((const char*)(gbase) + (voff)[_i]), (LAS unsigned*)(lds + (bufoff) + ldsw + _i * 8192), 16, 0, 0); } while (0)
; #define PG8_LDA(dst, b, h) do { _Pragma("unroll") for (int m = 0; m < 4; ++m) _Pragma("unroll") for (int k = 0; k < 2; ++k) dst[m][k] = *(const LAS bf16x8*)(lds + PG8_SA(b, h) + aoff + m * 2048 + k * 1024); } while (0)
; #define PG8_LDB(dst, b, h) do { _Pragma("unroll") for (int n = 0; n < 2; ++n) _Pragma("unroll") for (int k = 0; k < 2; ++k) dst[n][k] = *(const LAS bf16x8*)(lds + PG8_SB(b, h) + boff + n * 2048 + k * 1024); } while (0)
; #define PG8_MMA(ai, bj, At, Bt) do { __builtin_amdgcn_s_setprio(1); _Pragma("unroll") for (int m = 0; m < 4; ++m) _Pragma("unroll") for (int n = 0; n < 2; ++n) _Pragma("unroll") for (int k = 0; k < 2; ++k) \
;         acc[ai][bj][m][n] = __builtin_amdgcn_mfma_f32_16x16x32_bf16(Bt[n][k], At[m][k], acc[ai][bj][m][n], 0, 0, 0); __builtin_amdgcn_s_setprio(0); } while (0)
; #define PG8_WAIT_V(n) asm volatile("s_waitcnt vmcnt(" #n ")" ::: "memory")
; #define PG8_WAIT_L(n) asm volatile("s_waitcnt lgkmcnt(" #n ")" ::: "memory")
; #define PG8_BAR __builtin_amdgcn_s_barrier()
; #define PG8_SCHED __builtin_amdgcn_sched_barrier(0)
; template <class Epi, class Sched>
; __device__ __forceinline__ void gemm_phase(LAS unsigned char* lds, const Gemm g, const Sched& S, const Epi& E, const int wave_s) {
;     ...
;             PG8_WAIT_V(8); PG8_WAIT_L(0); PG8_BAR; PG8_MMA(1, 0, At, B0); PG8_MMA(1, 1, At, B1); PG8_BAR; PG8_SCHED;
;             PG8_LDB(B0, 1, 0); PG8_LDB(B1, 1, 1); PG8_SCHED; PG8_LDA(At, 1, 0); PG8_STAGE(PG8_SA(0, 1), a2 + hstepA, voffA);
;             PG8_WAIT_V(8); PG8_WAIT_L(0); PG8_BAR; PG8_MMA(0, 0, At, B0); PG8_MMA(0, 1, At, B1); PG8_BAR; PG8_SCHED;
	s_setprio 1
	v_mfma_f32_16x16x32_bf16 v[60:63], v[152:155], v[184:187], v[60:63]
	v_mfma_f32_16x16x32_bf16 v[56:59], v[160:163], v[184:187], v[56:59]
	v_mfma_f32_16x16x32_bf16 v[52:55], v[152:155], v[192:195], v[52:55]
	v_mfma_f32_16x16x32_bf16 v[44:47], v[160:163], v[192:195], v[44:47]
	v_mfma_f32_16x16x32_bf16 v[36:39], v[152:155], v[200:203], v[36:39]
	v_mfma_f32_16x16x32_bf16 v[28:31], v[160:163], v[200:203], v[28:31]
	v_mfma_f32_16x16x32_bf16 v[20:23], v[152:155], v[210:213], v[20:23]
	v_mfma_f32_16x16x32_bf16 v[12:15], v[160:163], v[210:213], v[12:15]
	v_mfma_f32_16x16x32_bf16 v[60:63], v[156:159], v[188:191], v[60:63]
	v_mfma_f32_16x16x32_bf16 v[56:59], v[164:167], v[188:191], v[56:59]
	v_mfma_f32_16x16x32_bf16 v[52:55], v[156:159], v[196:199], v[52:55]
	v_mfma_f32_16x16x32_bf16 v[44:47], v[164:167], v[196:199], v[44:47]
	v_mfma_f32_16x16x32_bf16 v[36:39], v[156:159], v[204:207], v[36:39]
	v_mfma_f32_16x16x32_bf16 v[28:31], v[164:167], v[204:207], v[28:31]
	v_mfma_f32_16x16x32_bf16 v[20:23], v[156:159], v[214:217], v[20:23]
	v_mfma_f32_16x16x32_bf16 v[12:15], v[164:167], v[214:217], v[12:15]
	s_nop 0
	s_nop 0
	v_mfma_f32_16x16x32_bf16 v[48:51], v[168:171], v[184:187], v[48:51]
	v_mfma_f32_16x16x32_bf16 v[40:43], v[176:179], v[184:187], v[40:43]
	v_mfma_f32_16x16x32_bf16 v[32:35], v[168:171], v[192:195], v[32:35]
	v_mfma_f32_16x16x32_bf16 v[24:27], v[176:179], v[192:195], v[24:27]
	v_mfma_f32_16x16x32_bf16 v[16:19], v[168:171], v[200:203], v[16:19]
	v_mfma_f32_16x16x32_bf16 v[8:11], v[176:179], v[200:203], v[8:11]
	v_mfma_f32_16x16x32_bf16 v[4:7], v[168:171], v[210:213], v[4:7]
	v_mfma_f32_16x16x32_bf16 v[0:3], v[176:179], v[210:213], v[0:3]
	v_mfma_f32_16x16x32_bf16 v[48:51], v[172:175], v[188:191], v[48:51]
	v_mfma_f32_16x16x32_bf16 v[40:43], v[180:183], v[188:191], v[40:43]
	v_mfma_f32_16x16x32_bf16 v[32:35], v[172:175], v[196:199], v[32:35]
	v_mfma_f32_16x16x32_bf16 v[24:27], v[180:183], v[196:199], v[24:27]
	v_mfma_f32_16x16x32_bf16 v[16:19], v[172:175], v[204:207], v[16:19]
	v_mfma_f32_16x16x32_bf16 v[8:11], v[180:183], v[204:207], v[8:11]
	v_mfma_f32_16x16x32_bf16 v[4:7], v[172:175], v[214:217], v[4:7]
	v_mfma_f32_16x16x32_bf16 v[0:3], v[180:183], v[214:217], v[0:3]
	s_setprio 0
	s_barrier
	s_add_i32 s66, 0, 0x18000
	s_add_i32 s67, 0, 0x1c000
	v_add_u32_e32 v164, s66, v147
	v_add_u32_e32 v180, s67, v147
	ds_read_b128 v[152:155], v164
	ds_read_b128 v[156:159], v164 offset:1024
	ds_read_b128 v[160:163], v164 offset:2048
	ds_read_b128 v[164:167], v164 offset:3072
	ds_read_b128 v[168:171], v180
	ds_read_b128 v[172:175], v180 offset:1024
	ds_read_b128 v[176:179], v180 offset:2048
	ds_read_b128 v[180:183], v180 offset:3072
	s_add_u32 s46, s46, 0x40000
	s_addc_u32 s47, s47, 0
	s_mov_b32 m0, s37
	v_lshl_add_u64 v[224:225], s[46:47], 0, v[128:129]
	ds_read_b128 v[184:187], v151 offset:32768
	ds_read_b128 v[188:191], v151 offset:33792
	ds_read_b128 v[192:195], v151 offset:34816
	ds_read_b128 v[196:199], v151 offset:35840
	ds_read_b128 v[200:203], v151 offset:36864
	ds_read_b128 v[204:207], v151 offset:37888
	ds_read_b128 v[210:213], v151 offset:38912
	ds_read_b128 v[214:217], v151 offset:39936
	global_load_lds_dwordx4 v[224:225], off
	v_lshl_add_u64 v[224:225], s[46:47], 0, v[132:133]
	s_mov_b32 m0, s43
	s_nop 0
	global_load_lds_dwordx4 v[224:225], off
	s_waitcnt vmcnt(8) lgkmcnt(0)
	s_barrier
	s_setprio 1
	v_mfma_f32_16x16x32_bf16 v[124:127], v[152:155], v[184:187], v[124:127]
	v_mfma_f32_16x16x32_bf16 v[120:123], v[160:163], v[184:187], v[120:123]
	v_mfma_f32_16x16x32_bf16 v[116:119], v[152:155], v[192:195], v[116:119]
	v_mfma_f32_16x16x32_bf16 v[108:111], v[160:163], v[192:195], v[108:111]
	v_mfma_f32_16x16x32_bf16 v[100:103], v[152:155], v[200:203], v[100:103]
	v_mfma_f32_16x16x32_bf16 v[92:95], v[160:163], v[200:203], v[92:95]
	v_mfma_f32_16x16x32_bf16 v[84:87], v[152:155], v[210:213], v[84:87]
	v_mfma_f32_16x16x32_bf16 v[76:79], v[160:163], v[210:213], v[76:79]
	v_mfma_f32_16x16x32_bf16 v[124:127], v[156:159], v[188:191], v[124:127]
	v_mfma_f32_16x16x32_bf16 v[120:123], v[164:167], v[188:191], v[120:123]
	v_mfma_f32_16x16x32_bf16 v[116:119], v[156:159], v[196:199], v[116:119]
	v_mfma_f32_16x16x32_bf16 v[108:111], v[164:167], v[196:199], v[108:111]
	v_mfma_f32_16x16x32_bf16 v[100:103], v[156:159], v[204:207], v[100:103]
	v_mfma_f32_16x16x32_bf16 v[92:95], v[164:167], v[204:207], v[92:95]
	v_mfma_f32_16x16x32_bf16 v[84:87], v[156:159], v[214:217], v[84:87]
	v_mfma_f32_16x16x32_bf16 v[76:79], v[164:167], v[214:217], v[76:79]
	s_nop 0
	s_nop 0
	v_mfma_f32_16x16x32_bf16 v[112:115], v[168:171], v[184:187], v[112:115]
	v_mfma_f32_16x16x32_bf16 v[104:107], v[176:179], v[184:187], v[104:107]
	v_mfma_f32_16x16x32_bf16 v[96:99], v[168:171], v[192:195], v[96:99]
	v_mfma_f32_16x16x32_bf16 v[88:91], v[176:179], v[192:195], v[88:91]
	v_mfma_f32_16x16x32_bf16 v[80:83], v[168:171], v[200:203], v[80:83]
	v_mfma_f32_16x16x32_bf16 v[72:75], v[176:179], v[200:203], v[72:75]
	v_mfma_f32_16x16x32_bf16 v[68:71], v[168:171], v[210:213], v[68:71]
	v_mfma_f32_16x16x32_bf16 v[64:67], v[176:179], v[210:213], v[64:67]
	v_mfma_f32_16x16x32_bf16 v[112:115], v[172:175], v[188:191], v[112:115]
	v_mfma_f32_16x16x32_bf16 v[104:107], v[180:183], v[188:191], v[104:107]
	v_mfma_f32_16x16x32_bf16 v[96:99], v[172:175], v[196:199], v[96:99]
	v_mfma_f32_16x16x32_bf16 v[88:91], v[180:183], v[196:199], v[88:91]
	v_mfma_f32_16x16x32_bf16 v[80:83], v[172:175], v[204:207], v[80:83]
	v_mfma_f32_16x16x32_bf16 v[72:75], v[180:183], v[204:207], v[72:75]
	v_mfma_f32_16x16x32_bf16 v[68:71], v[172:175], v[214:217], v[68:71]
	v_mfma_f32_16x16x32_bf16 v[64:67], v[180:183], v[214:217], v[64:67]
	s_setprio 0
	s_barrier
; #define PG8_STAGE(bufoff, gbase, voff) do { _Pragma("unroll") for (int _i = 0; _i < 2; ++_i) \
;         __builtin_amdgcn_global_load_lds((const unsigned*)((const char*)(gbase) + (voff)[_i]), (LAS unsigned*)(lds + (bufoff) + ldsw + _i * 8192), 16, 0, 0); } while (0)
; #define PG8_LDA(dst, b, h) do { _Pragma("unroll") for (int m = 0; m < 4; ++m) _Pragma("unroll") for (int k = 0; k < 2; ++k) dst[m][k] = *(const LAS bf16x8*)(lds + PG8_SA(b, h) + aoff + m * 2048 + k * 1024); } while (0)
; #define PG8_MMA(ai, bj, At, Bt) do { __builtin_amdgcn_s_setprio(1); _Pragma("unroll") for (int m = 0; m < 4; ++m) _Pragma("unroll") for (int n = 0; n < 2; ++n) _Pragma("unroll") for (int k = 0; k < 2; ++k) \
;         acc[ai][bj][m][n] = __builtin_amdgcn_mfma_f32_16x16x32_bf16(Bt[n][k], At[m][k], acc[ai][bj][m][n], 0, 0, 0); __builtin_amdgcn_s_setprio(0); } while (0)
; #define PG8_WAIT_V(n) asm volatile("s_waitcnt vmcnt(" #n ")" ::: "memory")
; #define PG8_WAIT_L(n) asm volatile("s_waitcnt lgkmcnt(" #n ")" ::: "memory")
; #define PG8_BAR __builtin_amdgcn_s_barrier()
; #define PG8_SCHED __builtin_amdgcn_sched_barrier(0)
; template <class Epi, class Sched>
; __device__ __forceinline__ void gemm_phase(LAS unsigned char* lds, const Gemm g, const Sched& S, const Epi& E, const int wave_s) {
;     ...
;             PG8_LDA(At, 1, 1); PG8_STAGE(PG8_SB(1, 0), b3, voffB); PG8_STAGE(PG8_SB(1, 1), b3 + hstepB, voffB); PG8_STAGE(PG8_SA(1, 0), a3, voffA);
;             PG8_WAIT_V(8); PG8_WAIT_L(0); PG8_BAR; PG8_MMA(1, 0, At, B0); PG8_MMA(1, 1, At, B1); PG8_BAR; PG8_SCHED;
;         }
;         if (wr == 0) PG8_BAR;
	s_add_i32 s46, s66, s81
	v_lshl_add_u64 v[144:145], v[144:145], 0, s[14:15]
	s_mov_b32 m0, s46
	ds_read_b128 v[184:187], v151 offset:49152
	ds_read_b128 v[188:191], v151 offset:50176
	ds_read_b128 v[192:195], v151 offset:51200
	ds_read_b128 v[196:199], v151 offset:52224
	ds_read_b128 v[200:203], v151 offset:53248
	ds_read_b128 v[204:207], v151 offset:54272
	ds_read_b128 v[210:213], v151 offset:55296
	ds_read_b128 v[214:217], v151 offset:56320
	global_load_lds_dwordx4 v[144:145], off
	s_add_i32 m0, s46, 0x2000
	s_add_u32 s4, s4, 0x40080
	v_lshl_add_u64 v[144:145], v[218:219], 0, s[14:15]
	s_addc_u32 s5, s5, 0
	s_add_i32 s46, s67, s81
	global_load_lds_dwordx4 v[144:145], off
	v_lshl_add_u64 v[144:145], s[4:5], 0, v[130:131]
	s_mov_b32 m0, s46
	s_nop 0
	global_load_lds_dwordx4 v[144:145], off
	v_lshl_add_u64 v[144:145], s[4:5], 0, v[134:135]
	s_add_i32 m0, s46, 0x2000
	s_nop 0
	global_load_lds_dwordx4 v[144:145], off
	v_lshl_add_u64 v[144:145], v[220:221], 0, s[14:15]
	s_mov_b32 m0, s49
	s_nop 0
	global_load_lds_dwordx4 v[144:145], off
	v_lshl_add_u64 v[144:145], v[222:223], 0, s[14:15]
	s_mov_b32 m0, s50
	s_nop 0
	global_load_lds_dwordx4 v[144:145], off
	s_waitcnt vmcnt(8) lgkmcnt(0)
	s_barrier
	s_setprio 1
	v_mfma_f32_16x16x32_bf16 v[60:63], v[152:155], v[184:187], v[60:63]
	v_mfma_f32_16x16x32_bf16 v[56:59], v[160:163], v[184:187], v[56:59]
	v_mfma_f32_16x16x32_bf16 v[52:55], v[152:155], v[192:195], v[52:55]
	v_mfma_f32_16x16x32_bf16 v[44:47], v[160:163], v[192:195], v[44:47]
	v_mfma_f32_16x16x32_bf16 v[36:39], v[152:155], v[200:203], v[36:39]
	v_mfma_f32_16x16x32_bf16 v[28:31], v[160:163], v[200:203], v[28:31]
	v_mfma_f32_16x16x32_bf16 v[20:23], v[152:155], v[210:213], v[20:23]
	v_mfma_f32_16x16x32_bf16 v[12:15], v[160:163], v[210:213], v[12:15]
	v_mfma_f32_16x16x32_bf16 v[60:63], v[156:159], v[188:191], v[60:63]
	v_mfma_f32_16x16x32_bf16 v[56:59], v[164:167], v[188:191], v[56:59]
	v_mfma_f32_16x16x32_bf16 v[52:55], v[156:159], v[196:199], v[52:55]
	v_mfma_f32_16x16x32_bf16 v[44:47], v[164:167], v[196:199], v[44:47]
	v_mfma_f32_16x16x32_bf16 v[36:39], v[156:159], v[204:207], v[36:39]
	v_mfma_f32_16x16x32_bf16 v[28:31], v[164:167], v[204:207], v[28:31]
	v_mfma_f32_16x16x32_bf16 v[20:23], v[156:159], v[214:217], v[20:23]
	v_mfma_f32_16x16x32_bf16 v[12:15], v[164:167], v[214:217], v[12:15]
	s_nop 0
	s_nop 0
	v_mfma_f32_16x16x32_bf16 v[48:51], v[168:171], v[184:187], v[48:51]
	v_mfma_f32_16x16x32_bf16 v[40:43], v[176:179], v[184:187], v[40:43]
	v_mfma_f32_16x16x32_bf16 v[32:35], v[168:171], v[192:195], v[32:35]
	v_mfma_f32_16x16x32_bf16 v[24:27], v[176:179], v[192:195], v[24:27]
	v_mfma_f32_16x16x32_bf16 v[16:19], v[168:171], v[200:203], v[16:19]
	v_mfma_f32_16x16x32_bf16 v[8:11], v[176:179], v[200:203], v[8:11]
	v_mfma_f32_16x16x32_bf16 v[4:7], v[168:171], v[210:213], v[4:7]
	v_mfma_f32_16x16x32_bf16 v[0:3], v[176:179], v[210:213], v[0:3]
	v_mfma_f32_16x16x32_bf16 v[48:51], v[172:175], v[188:191], v[48:51]
	v_mfma_f32_16x16x32_bf16 v[40:43], v[180:183], v[188:191], v[40:43]
	v_mfma_f32_16x16x32_bf16 v[32:35], v[172:175], v[196:199], v[32:35]
	v_mfma_f32_16x16x32_bf16 v[24:27], v[180:183], v[196:199], v[24:27]
	v_mfma_f32_16x16x32_bf16 v[16:19], v[172:175], v[204:207], v[16:19]
	v_mfma_f32_16x16x32_bf16 v[8:11], v[180:183], v[204:207], v[8:11]
	v_mfma_f32_16x16x32_bf16 v[4:7], v[172:175], v[214:217], v[4:7]
	v_mfma_f32_16x16x32_bf16 v[0:3], v[180:183], v[214:217], v[0:3]
	s_setprio 0
	s_barrier
	s_add_i32 s65, s65, 2
	s_add_u32 s44, s44, 0x100
	s_addc_u32 s45, s45, 0
	s_add_u32 s63, s63, 0x100
	s_addc_u32 s64, s64, 0
	s_cmp_gt_u32 s65, 13
	s_cbranch_scc0 .LBB0_125
	s_and_b64 vcc, exec, s[16:17]
	s_cbranch_vccz .LBB0_128
	s_barrier

; #define PG8_STAGE(bufoff, gbase, voff) do { _Pragma("unroll") for (int _i = 0; _i < 2; ++_i) \
;         __builtin_amdgcn_global_load_lds((const unsigned*)((const char*)(gbase) + (voff)[_i]), (LAS unsigned*)(lds + (bufoff) + ldsw + _i * 8192), 16, 0, 0); } while (0)
; #define PG8_LDA(dst, b, h) do { _Pragma("unroll") for (int m = 0; m < 4; ++m) _Pragma("unroll") for (int k = 0; k < 2; ++k) dst[m][k] = *(const LAS bf16x8*)(lds + PG8_SA(b, h) + aoff + m * 2048 + k * 1024); } while (0)
; #define PG8_LDB(dst, b, h) do { _Pragma("unroll") for (int n = 0; n < 2; ++n) _Pragma("unroll") for (int k = 0; k < 2; ++k) dst[n][k] = *(const LAS bf16x8*)(lds + PG8_SB(b, h) + boff + n * 2048 + k * 1024); } while (0)
; #define PG8_MMA(ai, bj, At, Bt) do { __builtin_amdgcn_s_setprio(1); _Pragma("unroll") for (int m = 0; m < 4; ++m) _Pragma("unroll") for (int n = 0; n < 2; ++n) _Pragma("unroll") for (int k = 0; k < 2; ++k) \
;         acc[ai][bj][m][n] = __builtin_amdgcn_mfma_f32_16x16x32_bf16(Bt[n][k], At[m][k], acc[ai][bj][m][n], 0, 0, 0); __builtin_amdgcn_s_setprio(0); } while (0)
; #define PG8_WAIT_V(n) asm volatile("s_waitcnt vmcnt(" #n ")" ::: "memory")
; #define PG8_WAIT_L(n) asm volatile("s_waitcnt lgkmcnt(" #n ")" ::: "memory")
; #define PG8_BAR __builtin_amdgcn_s_barrier()
; #define PG8_SCHED __builtin_amdgcn_sched_barrier(0)
; template <class Epi, class Sched>
; __device__ __forceinline__ void gemm_phase(LAS unsigned char* lds, const Gemm g, const Sched& S, const Epi& E, const int wave_s) {
;     ...
;             PG8_LDB(B0, 0, 0); PG8_LDB(B1, 0, 1); PG8_SCHED; PG8_LDA(At, 0, 0); PG8_STAGE(PG8_SA(1, 1), a1 + hstepA, voffA);
;             PG8_WAIT_V(8); PG8_WAIT_L(0); PG8_BAR; PG8_MMA(0, 0, At, B0); PG8_MMA(0, 1, At, B1); PG8_BAR; PG8_SCHED;
;             PG8_LDA(At, 0, 1); PG8_STAGE(PG8_SB(0, 0), b2, voffB); PG8_STAGE(PG8_SB(0, 1), b2 + hstepB, voffB); PG8_STAGE(PG8_SA(0, 0), a2, voffA);
;             PG8_WAIT_V(8); PG8_WAIT_L(0); PG8_BAR; PG8_MMA(1, 0, At, B0); PG8_MMA(1, 1, At, B1); PG8_BAR; PG8_SCHED;
.LBB0_194:
	ds_read_b128 v[144:147], v151
	ds_read_b128 v[154:157], v151 offset:1024
	ds_read_b128 v[158:161], v151 offset:2048
	ds_read_b128 v[162:165], v151 offset:3072
	ds_read_b128 v[166:169], v152
	ds_read_b128 v[170:173], v152 offset:1024
	ds_read_b128 v[174:177], v152 offset:2048
	ds_read_b128 v[178:181], v152 offset:3072
	s_add_u32 s4, s24, 0xfffc0080
	s_addc_u32 s5, s25, -1
	s_cmp_eq_u32 s54, 12
	s_cselect_b32 s27, s19, s5
	s_cselect_b32 s26, s50, s4
	s_cselect_b32 s5, s17, s53
	s_cselect_b32 s4, s51, s52
	v_lshl_add_u64 v[206:207], s[24:25], 0, v[136:137]
	s_add_i32 m0, s30, 0xc000
	ds_read_b128 v[182:185], v153
	ds_read_b128 v[186:189], v153 offset:1024
	ds_read_b128 v[190:193], v153 offset:2048
	ds_read_b128 v[194:197], v153 offset:3072
	ds_read_b128 v[198:201], v153 offset:4096
	ds_read_b128 v[202:205], v153 offset:5120
	ds_read_b128 v[210:213], v153 offset:6144
	ds_read_b128 v[214:217], v153 offset:7168
	global_load_lds_dwordx4 v[206:207], off
	v_lshl_add_u64 v[206:207], s[24:25], 0, v[138:139]
	s_add_i32 m0, s30, 0xe000
	s_nop 0
	global_load_lds_dwordx4 v[206:207], off
	s_waitcnt vmcnt(8) lgkmcnt(0)
	s_barrier
	s_setprio 1
	v_mfma_f32_16x16x32_bf16 v[124:127], v[144:147], v[182:185], v[124:127]
	v_mfma_f32_16x16x32_bf16 v[120:123], v[158:161], v[182:185], v[120:123]
	v_mfma_f32_16x16x32_bf16 v[116:119], v[144:147], v[190:193], v[116:119]
	v_mfma_f32_16x16x32_bf16 v[108:111], v[158:161], v[190:193], v[108:111]
	v_mfma_f32_16x16x32_bf16 v[100:103], v[144:147], v[198:201], v[100:103]
	v_mfma_f32_16x16x32_bf16 v[92:95], v[158:161], v[198:201], v[92:95]
	v_mfma_f32_16x16x32_bf16 v[84:87], v[144:147], v[210:213], v[84:87]
	v_mfma_f32_16x16x32_bf16 v[76:79], v[158:161], v[210:213], v[76:79]
	v_mfma_f32_16x16x32_bf16 v[124:127], v[154:157], v[186:189], v[124:127]
	v_mfma_f32_16x16x32_bf16 v[120:123], v[162:165], v[186:189], v[120:123]
	v_mfma_f32_16x16x32_bf16 v[116:119], v[154:157], v[194:197], v[116:119]
	v_mfma_f32_16x16x32_bf16 v[108:111], v[162:165], v[194:197], v[108:111]
	v_mfma_f32_16x16x32_bf16 v[100:103], v[154:157], v[202:205], v[100:103]
	v_mfma_f32_16x16x32_bf16 v[92:95], v[162:165], v[202:205], v[92:95]
	v_mfma_f32_16x16x32_bf16 v[84:87], v[154:157], v[214:217], v[84:87]
	v_mfma_f32_16x16x32_bf16 v[76:79], v[162:165], v[214:217], v[76:79]
	s_nop 0
	s_nop 0
	v_mfma_f32_16x16x32_bf16 v[112:115], v[166:169], v[182:185], v[112:115]
	v_mfma_f32_16x16x32_bf16 v[104:107], v[174:177], v[182:185], v[104:107]
	v_mfma_f32_16x16x32_bf16 v[96:99], v[166:169], v[190:193], v[96:99]
	v_mfma_f32_16x16x32_bf16 v[88:91], v[174:177], v[190:193], v[88:91]
	v_mfma_f32_16x16x32_bf16 v[80:83], v[166:169], v[198:201], v[80:83]
	v_mfma_f32_16x16x32_bf16 v[72:75], v[174:177], v[198:201], v[72:75]
	v_mfma_f32_16x16x32_bf16 v[68:71], v[166:169], v[210:213], v[68:71]
	v_mfma_f32_16x16x32_bf16 v[64:67], v[174:177], v[210:213], v[64:67]
	v_mfma_f32_16x16x32_bf16 v[112:115], v[170:173], v[186:189], v[112:115]
	v_mfma_f32_16x16x32_bf16 v[104:107], v[178:181], v[186:189], v[104:107]
	v_mfma_f32_16x16x32_bf16 v[96:99], v[170:173], v[194:197], v[96:99]
	v_mfma_f32_16x16x32_bf16 v[88:91], v[178:181], v[194:197], v[88:91]
	v_mfma_f32_16x16x32_bf16 v[80:83], v[170:173], v[202:205], v[80:83]
	v_mfma_f32_16x16x32_bf16 v[72:75], v[178:181], v[202:205], v[72:75]
	v_mfma_f32_16x16x32_bf16 v[68:71], v[170:173], v[214:217], v[68:71]
	v_mfma_f32_16x16x32_bf16 v[64:67], v[178:181], v[214:217], v[64:67]
	s_setprio 0
	s_barrier
	s_add_i32 s55, s45, s81
	v_lshl_add_u64 v[206:207], s[4:5], 0, v[132:133]
	s_mov_b32 m0, s55
	ds_read_b128 v[182:185], v153 offset:16384
	ds_read_b128 v[186:189], v153 offset:17408
	ds_read_b128 v[190:193], v153 offset:18432
	ds_read_b128 v[194:197], v153 offset:19456
	ds_read_b128 v[198:201], v153 offset:20480
	ds_read_b128 v[202:205], v153 offset:21504
	ds_read_b128 v[210:213], v153 offset:22528
	ds_read_b128 v[214:217], v153 offset:23552
	global_load_lds_dwordx4 v[206:207], off
	s_add_i32 m0, s55, 0x2000
	s_add_u32 s58, s4, 0x40000
	v_lshl_add_u64 v[218:219], s[4:5], 0, v[128:129]
	s_addc_u32 s59, s5, 0
	s_add_i32 s55, s46, s81
	global_load_lds_dwordx4 v[218:219], off
	v_lshl_add_u64 v[220:221], s[58:59], 0, v[132:133]
	s_mov_b32 m0, s55
	v_lshl_add_u64 v[222:223], s[26:27], 0, v[130:131]
	global_load_lds_dwordx4 v[220:221], off
	v_lshl_add_u64 v[220:221], s[58:59], 0, v[128:129]
	s_add_i32 m0, s55, 0x2000
	s_nop 0
	global_load_lds_dwordx4 v[220:221], off
	v_lshl_add_u64 v[220:221], s[26:27], 0, v[134:135]
	s_mov_b32 m0, s30
	s_nop 0
	global_load_lds_dwordx4 v[220:221], off
	s_mov_b32 m0, s31
	s_nop 0
	global_load_lds_dwordx4 v[222:223], off
	s_waitcnt vmcnt(8) lgkmcnt(0)
	s_barrier
; #define PG8_STAGE(bufoff, gbase, voff) do { _Pragma("unroll") for (int _i = 0; _i < 2; ++_i) \
;         __builtin_amdgcn_global_load_lds((const unsigned*)((const char*)(gbase) + (voff)[_i]), (LAS unsigned*)(lds + (bufoff) + ldsw + _i * 8192), 16, 0, 0); } while (0)
; #define PG8_LDA(dst, b, h) do { _Pragma("unroll") for (int m = 0; m < 4; ++m) _Pragma("unroll") for (int k = 0; k < 2; ++k) dst[m][k] = *(const LAS bf16x8*)(lds + PG8_SA(b, h) + aoff + m * 2048 + k * 1024); } while (0)
; #define PG8_LDB(dst, b, h) do { _Pragma("unroll") for (int n = 0; n < 2; ++n) _Pragma("unroll") for (int k = 0; k < 2; ++k) dst[n][k] = *(const LAS bf16x8*)(lds + PG8_SB(b, h) + boff + n * 2048 + k * 1024); } while (0)
; #define PG8_MMA(ai, bj, At, Bt) do { __builtin_amdgcn_s_setprio(1); _Pragma("unroll") for (int m = 0; m < 4; ++m) _Pragma("unroll") for (int n = 0; n < 2; ++n) _Pragma("unroll") for (int k = 0; k < 2; ++k) \
;         acc[ai][bj][m][n] = __builtin_amdgcn_mfma_f32_16x16x32_bf16(Bt[n][k], At[m][k], acc[ai][bj][m][n], 0, 0, 0); __builtin_amdgcn_s_setprio(0); } while (0)
; #define PG8_WAIT_V(n) asm volatile("s_waitcnt vmcnt(" #n ")" ::: "memory")
; #define PG8_WAIT_L(n) asm volatile("s_waitcnt lgkmcnt(" #n ")" ::: "memory")
; #define PG8_BAR __builtin_amdgcn_s_barrier()
; #define PG8_SCHED __builtin_amdgcn_sched_barrier(0)
; template <class Epi, class Sched>
; __device__ __forceinline__ void gemm_phase(LAS unsigned char* lds, const Gemm g, const Sched& S, const Epi& E, const int wave_s) {
;     ...
;             PG8_WAIT_V(8); PG8_WAIT_L(0); PG8_BAR; PG8_MMA(1, 0, At, B0); PG8_MMA(1, 1, At, B1); PG8_BAR; PG8_SCHED;
;             PG8_LDB(B0, 1, 0); PG8_LDB(B1, 1, 1); PG8_SCHED; PG8_LDA(At, 1, 0); PG8_STAGE(PG8_SA(0, 1), a2 + hstepA, voffA);
;             PG8_WAIT_V(8); PG8_WAIT_L(0); PG8_BAR; PG8_MMA(0, 0, At, B0); PG8_MMA(0, 1, At, B1); PG8_BAR; PG8_SCHED;
	s_setprio 1
	v_mfma_f32_16x16x32_bf16 v[60:63], v[144:147], v[182:185], v[60:63]
	v_mfma_f32_16x16x32_bf16 v[56:59], v[158:161], v[182:185], v[56:59]
	v_mfma_f32_16x16x32_bf16 v[52:55], v[144:147], v[190:193], v[52:55]
	v_mfma_f32_16x16x32_bf16 v[44:47], v[158:161], v[190:193], v[44:47]
	v_mfma_f32_16x16x32_bf16 v[36:39], v[144:147], v[198:201], v[36:39]
	v_mfma_f32_16x16x32_bf16 v[28:31], v[158:161], v[198:201], v[28:31]
	v_mfma_f32_16x16x32_bf16 v[20:23], v[144:147], v[210:213], v[20:23]
	v_mfma_f32_16x16x32_bf16 v[12:15], v[158:161], v[210:213], v[12:15]
	v_mfma_f32_16x16x32_bf16 v[60:63], v[154:157], v[186:189], v[60:63]
	v_mfma_f32_16x16x32_bf16 v[56:59], v[162:165], v[186:189], v[56:59]
	v_mfma_f32_16x16x32_bf16 v[52:55], v[154:157], v[194:197], v[52:55]
	v_mfma_f32_16x16x32_bf16 v[44:47], v[162:165], v[194:197], v[44:47]
	v_mfma_f32_16x16x32_bf16 v[36:39], v[154:157], v[202:205], v[36:39]
	v_mfma_f32_16x16x32_bf16 v[28:31], v[162:165], v[202:205], v[28:31]
	v_mfma_f32_16x16x32_bf16 v[20:23], v[154:157], v[214:217], v[20:23]
	v_mfma_f32_16x16x32_bf16 v[12:15], v[162:165], v[214:217], v[12:15]
	s_nop 0
	s_nop 0
	v_mfma_f32_16x16x32_bf16 v[48:51], v[166:169], v[182:185], v[48:51]
	v_mfma_f32_16x16x32_bf16 v[40:43], v[174:177], v[182:185], v[40:43]
	v_mfma_f32_16x16x32_bf16 v[32:35], v[166:169], v[190:193], v[32:35]
	v_mfma_f32_16x16x32_bf16 v[24:27], v[174:177], v[190:193], v[24:27]
	v_mfma_f32_16x16x32_bf16 v[16:19], v[166:169], v[198:201], v[16:19]
	v_mfma_f32_16x16x32_bf16 v[8:11], v[174:177], v[198:201], v[8:11]
	v_mfma_f32_16x16x32_bf16 v[4:7], v[166:169], v[210:213], v[4:7]
	v_mfma_f32_16x16x32_bf16 v[0:3], v[174:177], v[210:213], v[0:3]
	v_mfma_f32_16x16x32_bf16 v[48:51], v[170:173], v[186:189], v[48:51]
	v_mfma_f32_16x16x32_bf16 v[40:43], v[178:181], v[186:189], v[40:43]
	v_mfma_f32_16x16x32_bf16 v[32:35], v[170:173], v[194:197], v[32:35]
	v_mfma_f32_16x16x32_bf16 v[24:27], v[178:181], v[194:197], v[24:27]
	v_mfma_f32_16x16x32_bf16 v[16:19], v[170:173], v[202:205], v[16:19]
	v_mfma_f32_16x16x32_bf16 v[8:11], v[178:181], v[202:205], v[8:11]
	v_mfma_f32_16x16x32_bf16 v[4:7], v[170:173], v[214:217], v[4:7]
	v_mfma_f32_16x16x32_bf16 v[0:3], v[178:181], v[214:217], v[0:3]
	s_setprio 0
	s_barrier
	s_add_i32 s55, 0, 0x18000
	s_add_i32 s57, 0, 0x1c000
	v_add_u32_e32 v162, s55, v149
	v_add_u32_e32 v178, s57, v149
	ds_read_b128 v[144:147], v162
	ds_read_b128 v[154:157], v162 offset:1024
	ds_read_b128 v[158:161], v162 offset:2048
	ds_read_b128 v[162:165], v162 offset:3072
	ds_read_b128 v[166:169], v178
	ds_read_b128 v[170:173], v178 offset:1024
	ds_read_b128 v[174:177], v178 offset:2048
	ds_read_b128 v[178:181], v178 offset:3072
	s_add_u32 s26, s26, 0x40000
	s_addc_u32 s27, s27, 0
	s_mov_b32 m0, s33
	v_lshl_add_u64 v[224:225], s[26:27], 0, v[134:135]
	ds_read_b128 v[182:185], v153 offset:32768
	ds_read_b128 v[186:189], v153 offset:33792
	ds_read_b128 v[190:193], v153 offset:34816
	ds_read_b128 v[194:197], v153 offset:35840
	ds_read_b128 v[198:201], v153 offset:36864
	ds_read_b128 v[202:205], v153 offset:37888
	ds_read_b128 v[210:213], v153 offset:38912
	ds_read_b128 v[214:217], v153 offset:39936
	global_load_lds_dwordx4 v[224:225], off
	v_lshl_add_u64 v[224:225], s[26:27], 0, v[130:131]
	s_mov_b32 m0, s35
	s_nop 0
	global_load_lds_dwordx4 v[224:225], off
	s_waitcnt vmcnt(8) lgkmcnt(0)
	s_barrier
	s_setprio 1
	v_mfma_f32_16x16x32_bf16 v[124:127], v[144:147], v[182:185], v[124:127]
	v_mfma_f32_16x16x32_bf16 v[120:123], v[158:161], v[182:185], v[120:123]
	v_mfma_f32_16x16x32_bf16 v[116:119], v[144:147], v[190:193], v[116:119]
	v_mfma_f32_16x16x32_bf16 v[108:111], v[158:161], v[190:193], v[108:111]
	v_mfma_f32_16x16x32_bf16 v[100:103], v[144:147], v[198:201], v[100:103]
	v_mfma_f32_16x16x32_bf16 v[92:95], v[158:161], v[198:201], v[92:95]
	v_mfma_f32_16x16x32_bf16 v[84:87], v[144:147], v[210:213], v[84:87]
	v_mfma_f32_16x16x32_bf16 v[76:79], v[158:161], v[210:213], v[76:79]
	v_mfma_f32_16x16x32_bf16 v[124:127], v[154:157], v[186:189], v[124:127]
	v_mfma_f32_16x16x32_bf16 v[120:123], v[162:165], v[186:189], v[120:123]
	v_mfma_f32_16x16x32_bf16 v[116:119], v[154:157], v[194:197], v[116:119]
	v_mfma_f32_16x16x32_bf16 v[108:111], v[162:165], v[194:197], v[108:111]
	v_mfma_f32_16x16x32_bf16 v[100:103], v[154:157], v[202:205], v[100:103]
	v_mfma_f32_16x16x32_bf16 v[92:95], v[162:165], v[202:205], v[92:95]
	v_mfma_f32_16x16x32_bf16 v[84:87], v[154:157], v[214:217], v[84:87]
	v_mfma_f32_16x16x32_bf16 v[76:79], v[162:165], v[214:217], v[76:79]
	s_nop 0
	s_nop 0
	v_mfma_f32_16x16x32_bf16 v[112:115], v[166:169], v[182:185], v[112:115]
	v_mfma_f32_16x16x32_bf16 v[104:107], v[174:177], v[182:185], v[104:107]
	v_mfma_f32_16x16x32_bf16 v[96:99], v[166:169], v[190:193], v[96:99]
	v_mfma_f32_16x16x32_bf16 v[88:91], v[174:177], v[190:193], v[88:91]
	v_mfma_f32_16x16x32_bf16 v[80:83], v[166:169], v[198:201], v[80:83]
	v_mfma_f32_16x16x32_bf16 v[72:75], v[174:177], v[198:201], v[72:75]
	v_mfma_f32_16x16x32_bf16 v[68:71], v[166:169], v[210:213], v[68:71]
	v_mfma_f32_16x16x32_bf16 v[64:67], v[174:177], v[210:213], v[64:67]
	v_mfma_f32_16x16x32_bf16 v[112:115], v[170:173], v[186:189], v[112:115]
	v_mfma_f32_16x16x32_bf16 v[104:107], v[178:181], v[186:189], v[104:107]
	v_mfma_f32_16x16x32_bf16 v[96:99], v[170:173], v[194:197], v[96:99]
	v_mfma_f32_16x16x32_bf16 v[88:91], v[178:181], v[194:197], v[88:91]
	v_mfma_f32_16x16x32_bf16 v[80:83], v[170:173], v[202:205], v[80:83]
	v_mfma_f32_16x16x32_bf16 v[72:75], v[178:181], v[202:205], v[72:75]
	v_mfma_f32_16x16x32_bf16 v[68:71], v[170:173], v[214:217], v[68:71]
	v_mfma_f32_16x16x32_bf16 v[64:67], v[178:181], v[214:217], v[64:67]
	s_setprio 0
	s_barrier
; #define PG8_STAGE(bufoff, gbase, voff) do { _Pragma("unroll") for (int _i = 0; _i < 2; ++_i) \
;         __builtin_amdgcn_global_load_lds((const unsigned*)((const char*)(gbase) + (voff)[_i]), (LAS unsigned*)(lds + (bufoff) + ldsw + _i * 8192), 16, 0, 0); } while (0)
; #define PG8_LDA(dst, b, h) do { _Pragma("unroll") for (int m = 0; m < 4; ++m) _Pragma("unroll") for (int k = 0; k < 2; ++k) dst[m][k] = *(const LAS bf16x8*)(lds + PG8_SA(b, h) + aoff + m * 2048 + k * 1024); } while (0)
; #define PG8_MMA(ai, bj, At, Bt) do { __builtin_amdgcn_s_setprio(1); _Pragma("unroll") for (int m = 0; m < 4; ++m) _Pragma("unroll") for (int n = 0; n < 2; ++n) _Pragma("unroll") for (int k = 0; k < 2; ++k) \
;         acc[ai][bj][m][n] = __builtin_amdgcn_mfma_f32_16x16x32_bf16(Bt[n][k], At[m][k], acc[ai][bj][m][n], 0, 0, 0); __builtin_amdgcn_s_setprio(0); } while (0)
; #define PG8_WAIT_V(n) asm volatile("s_waitcnt vmcnt(" #n ")" ::: "memory")
; #define PG8_WAIT_L(n) asm volatile("s_waitcnt lgkmcnt(" #n ")" ::: "memory")
; #define PG8_BAR __builtin_amdgcn_s_barrier()
; #define PG8_SCHED __builtin_amdgcn_sched_barrier(0)
; template <class Epi, class Sched>
; __device__ __forceinline__ void gemm_phase(LAS unsigned char* lds, const Gemm g, const Sched& S, const Epi& E, const int wave_s) {
;     ...
;             PG8_LDA(At, 1, 1); PG8_STAGE(PG8_SB(1, 0), b3, voffB); PG8_STAGE(PG8_SB(1, 1), b3 + hstepB, voffB); PG8_STAGE(PG8_SA(1, 0), a3, voffA);
;             PG8_WAIT_V(8); PG8_WAIT_L(0); PG8_BAR; PG8_MMA(1, 0, At, B0); PG8_MMA(1, 1, At, B1); PG8_BAR; PG8_SCHED;
;         }
;         if (wr == 0) PG8_BAR;
	s_add_i32 s26, s55, s81
	v_lshl_add_u64 v[206:207], v[206:207], 0, s[12:13]
	s_mov_b32 m0, s26
	ds_read_b128 v[182:185], v153 offset:49152
	ds_read_b128 v[186:189], v153 offset:50176
	ds_read_b128 v[190:193], v153 offset:51200
	ds_read_b128 v[194:197], v153 offset:52224
	ds_read_b128 v[198:201], v153 offset:53248
	ds_read_b128 v[202:205], v153 offset:54272
	ds_read_b128 v[210:213], v153 offset:55296
	ds_read_b128 v[214:217], v153 offset:56320
	global_load_lds_dwordx4 v[206:207], off
	s_add_i32 m0, s26, 0x2000
	s_add_u32 s4, s4, 0x40080
	v_lshl_add_u64 v[206:207], v[218:219], 0, s[12:13]
	s_addc_u32 s5, s5, 0
	s_add_i32 s26, s57, s81
	global_load_lds_dwordx4 v[206:207], off
	v_lshl_add_u64 v[206:207], s[4:5], 0, v[132:133]
	s_mov_b32 m0, s26
	s_nop 0
	global_load_lds_dwordx4 v[206:207], off
	v_lshl_add_u64 v[206:207], s[4:5], 0, v[128:129]
	s_add_i32 m0, s26, 0x2000
	s_nop 0
	global_load_lds_dwordx4 v[206:207], off
	v_lshl_add_u64 v[206:207], v[220:221], 0, s[12:13]
	s_mov_b32 m0, s41
	s_nop 0
	global_load_lds_dwordx4 v[206:207], off
	v_lshl_add_u64 v[206:207], v[222:223], 0, s[12:13]
	s_mov_b32 m0, s42
	s_nop 0
	global_load_lds_dwordx4 v[206:207], off
	s_waitcnt vmcnt(8) lgkmcnt(0)
	s_barrier
	s_setprio 1
	v_mfma_f32_16x16x32_bf16 v[60:63], v[144:147], v[182:185], v[60:63]
	v_mfma_f32_16x16x32_bf16 v[56:59], v[158:161], v[182:185], v[56:59]
	v_mfma_f32_16x16x32_bf16 v[52:55], v[144:147], v[190:193], v[52:55]
	v_mfma_f32_16x16x32_bf16 v[44:47], v[158:161], v[190:193], v[44:47]
	v_mfma_f32_16x16x32_bf16 v[36:39], v[144:147], v[198:201], v[36:39]
	v_mfma_f32_16x16x32_bf16 v[28:31], v[158:161], v[198:201], v[28:31]
	v_mfma_f32_16x16x32_bf16 v[20:23], v[144:147], v[210:213], v[20:23]
	v_mfma_f32_16x16x32_bf16 v[12:15], v[158:161], v[210:213], v[12:15]
	v_mfma_f32_16x16x32_bf16 v[60:63], v[154:157], v[186:189], v[60:63]
	v_mfma_f32_16x16x32_bf16 v[56:59], v[162:165], v[186:189], v[56:59]
	v_mfma_f32_16x16x32_bf16 v[52:55], v[154:157], v[194:197], v[52:55]
	v_mfma_f32_16x16x32_bf16 v[44:47], v[162:165], v[194:197], v[44:47]
	v_mfma_f32_16x16x32_bf16 v[36:39], v[154:157], v[202:205], v[36:39]
	v_mfma_f32_16x16x32_bf16 v[28:31], v[162:165], v[202:205], v[28:31]
	v_mfma_f32_16x16x32_bf16 v[20:23], v[154:157], v[214:217], v[20:23]
	v_mfma_f32_16x16x32_bf16 v[12:15], v[162:165], v[214:217], v[12:15]
	s_nop 0
	s_nop 0
	v_mfma_f32_16x16x32_bf16 v[48:51], v[166:169], v[182:185], v[48:51]
	v_mfma_f32_16x16x32_bf16 v[40:43], v[174:177], v[182:185], v[40:43]
	v_mfma_f32_16x16x32_bf16 v[32:35], v[166:169], v[190:193], v[32:35]
	v_mfma_f32_16x16x32_bf16 v[24:27], v[174:177], v[190:193], v[24:27]
	v_mfma_f32_16x16x32_bf16 v[16:19], v[166:169], v[198:201], v[16:19]
	v_mfma_f32_16x16x32_bf16 v[8:11], v[174:177], v[198:201], v[8:11]
	v_mfma_f32_16x16x32_bf16 v[4:7], v[166:169], v[210:213], v[4:7]
	v_mfma_f32_16x16x32_bf16 v[0:3], v[174:177], v[210:213], v[0:3]
	v_mfma_f32_16x16x32_bf16 v[48:51], v[170:173], v[186:189], v[48:51]
	v_mfma_f32_16x16x32_bf16 v[40:43], v[178:181], v[186:189], v[40:43]
	v_mfma_f32_16x16x32_bf16 v[32:35], v[170:173], v[194:197], v[32:35]
	v_mfma_f32_16x16x32_bf16 v[24:27], v[178:181], v[194:197], v[24:27]
	v_mfma_f32_16x16x32_bf16 v[16:19], v[170:173], v[202:205], v[16:19]
	v_mfma_f32_16x16x32_bf16 v[8:11], v[178:181], v[202:205], v[8:11]
	v_mfma_f32_16x16x32_bf16 v[4:7], v[170:173], v[214:217], v[4:7]
	v_mfma_f32_16x16x32_bf16 v[0:3], v[178:181], v[214:217], v[0:3]
	s_setprio 0
	s_barrier
	s_add_i32 s54, s54, 2
	s_add_u32 s24, s24, 0x100
	s_addc_u32 s25, s25, 0
	s_add_u32 s52, s52, 0x100
	s_addc_u32 s53, s53, 0
	s_cmp_gt_u32 s54, 13
	s_cbranch_scc0 .LBB0_194
	s_and_b64 vcc, exec, s[14:15]
	s_cbranch_vccz .LBB0_197
	s_barrier

; #define PG8_STAGE(bufoff, gbase, voff) do { _Pragma("unroll") for (int _i = 0; _i < 2; ++_i) \
;         __builtin_amdgcn_global_load_lds((const unsigned*)((const char*)(gbase) + (voff)[_i]), (LAS unsigned*)(lds + (bufoff) + ldsw + _i * 8192), 16, 0, 0); } while (0)
; #define PG8_LDA(dst, b, h) do { _Pragma("unroll") for (int m = 0; m < 4; ++m) _Pragma("unroll") for (int k = 0; k < 2; ++k) dst[m][k] = *(const LAS bf16x8*)(lds + PG8_SA(b, h) + aoff + m * 2048 + k * 1024); } while (0)
; #define PG8_LDB(dst, b, h) do { _Pragma("unroll") for (int n = 0; n < 2; ++n) _Pragma("unroll") for (int k = 0; k < 2; ++k) dst[n][k] = *(const LAS bf16x8*)(lds + PG8_SB(b, h) + boff + n * 2048 + k * 1024); } while (0)
; #define PG8_MMA(ai, bj, At, Bt) do { __builtin_amdgcn_s_setprio(1); _Pragma("unroll") for (int m = 0; m < 4; ++m) _Pragma("unroll") for (int n = 0; n < 2; ++n) _Pragma("unroll") for (int k = 0; k < 2; ++k) \
;         acc[ai][bj][m][n] = __builtin_amdgcn_mfma_f32_16x16x32_bf16(Bt[n][k], At[m][k], acc[ai][bj][m][n], 0, 0, 0); __builtin_amdgcn_s_setprio(0); } while (0)
; #define PG8_WAIT_V(n) asm volatile("s_waitcnt vmcnt(" #n ")" ::: "memory")
; #define PG8_WAIT_L(n) asm volatile("s_waitcnt lgkmcnt(" #n ")" ::: "memory")
; #define PG8_BAR __builtin_amdgcn_s_barrier()
; #define PG8_SCHED __builtin_amdgcn_sched_barrier(0)
; template <class Epi, class Sched>
; __device__ __forceinline__ void gemm_phase(LAS unsigned char* lds, const Gemm g, const Sched& S, const Epi& E, const int wave_s) {
;     ...
;             PG8_LDB(B0, 0, 0); PG8_LDB(B1, 0, 1); PG8_SCHED; PG8_LDA(At, 0, 0); PG8_STAGE(PG8_SA(1, 1), a1 + hstepA, voffA);
;             PG8_WAIT_V(8); PG8_WAIT_L(0); PG8_BAR; PG8_MMA(0, 0, At, B0); PG8_MMA(0, 1, At, B1); PG8_BAR; PG8_SCHED;
;             PG8_LDA(At, 0, 1); PG8_STAGE(PG8_SB(0, 0), b2, voffB); PG8_STAGE(PG8_SB(0, 1), b2 + hstepB, voffB); PG8_STAGE(PG8_SA(0, 0), a2, voffA);
;             PG8_WAIT_V(8); PG8_WAIT_L(0); PG8_BAR; PG8_MMA(1, 0, At, B0); PG8_MMA(1, 1, At, B1); PG8_BAR; PG8_SCHED;
.LBB0_375:
	ds_read_b128 v[158:161], v155
	ds_read_b128 v[162:165], v155 offset:1024
	ds_read_b128 v[166:169], v155 offset:2048
	ds_read_b128 v[170:173], v155 offset:3072
	ds_read_b128 v[174:177], v156
	ds_read_b128 v[178:181], v156 offset:1024
	ds_read_b128 v[182:185], v156 offset:2048
	ds_read_b128 v[186:189], v156 offset:3072
	s_add_u32 s4, s22, 0x100
	s_addc_u32 s5, s23, 0
	s_cmp_eq_u32 s48, 2
	s_cselect_b32 s25, s19, s5
	s_cselect_b32 s24, s18, s4
	s_cselect_b32 s9, s21, s47
	s_cselect_b32 s8, s20, s46
	v_lshl_add_u64 v[150:151], s[22:23], 0, v[142:143]
	s_add_i32 m0, s27, 0xc000
	ds_read_b128 v[190:193], v157
	ds_read_b128 v[194:197], v157 offset:1024
	ds_read_b128 v[198:201], v157 offset:2048
	ds_read_b128 v[202:205], v157 offset:3072
	ds_read_b128 v[210:213], v157 offset:4096
	ds_read_b128 v[214:217], v157 offset:5120
	ds_read_b128 v[218:221], v157 offset:6144
	ds_read_b128 v[222:225], v157 offset:7168
	global_load_lds_dwordx4 v[150:151], off
	v_lshl_add_u64 v[150:151], s[22:23], 0, v[144:145]
	s_add_i32 m0, s27, 0xe000
	s_nop 0
	global_load_lds_dwordx4 v[150:151], off
	s_waitcnt vmcnt(8) lgkmcnt(0)
	s_barrier
	s_setprio 1
	v_mfma_f32_16x16x32_bf16 v[124:127], v[158:161], v[190:193], v[124:127]
	v_mfma_f32_16x16x32_bf16 v[120:123], v[166:169], v[190:193], v[120:123]
	v_mfma_f32_16x16x32_bf16 v[108:111], v[158:161], v[198:201], v[108:111]
	v_mfma_f32_16x16x32_bf16 v[104:107], v[166:169], v[198:201], v[104:107]
	v_mfma_f32_16x16x32_bf16 v[92:95], v[158:161], v[210:213], v[92:95]
	v_mfma_f32_16x16x32_bf16 v[88:91], v[166:169], v[210:213], v[88:91]
	v_mfma_f32_16x16x32_bf16 v[76:79], v[158:161], v[218:221], v[76:79]
	v_mfma_f32_16x16x32_bf16 v[72:75], v[166:169], v[218:221], v[72:75]
	v_mfma_f32_16x16x32_bf16 v[124:127], v[162:165], v[194:197], v[124:127]
	v_mfma_f32_16x16x32_bf16 v[120:123], v[170:173], v[194:197], v[120:123]
	v_mfma_f32_16x16x32_bf16 v[108:111], v[162:165], v[202:205], v[108:111]
	v_mfma_f32_16x16x32_bf16 v[104:107], v[170:173], v[202:205], v[104:107]
	v_mfma_f32_16x16x32_bf16 v[92:95], v[162:165], v[214:217], v[92:95]
	v_mfma_f32_16x16x32_bf16 v[88:91], v[170:173], v[214:217], v[88:91]
	v_mfma_f32_16x16x32_bf16 v[76:79], v[162:165], v[222:225], v[76:79]
	v_mfma_f32_16x16x32_bf16 v[72:75], v[170:173], v[222:225], v[72:75]
	s_nop 0
	s_nop 0
	v_mfma_f32_16x16x32_bf16 v[116:119], v[174:177], v[190:193], v[116:119]
	v_mfma_f32_16x16x32_bf16 v[112:115], v[182:185], v[190:193], v[112:115]
	v_mfma_f32_16x16x32_bf16 v[100:103], v[174:177], v[198:201], v[100:103]
	v_mfma_f32_16x16x32_bf16 v[96:99], v[182:185], v[198:201], v[96:99]
	v_mfma_f32_16x16x32_bf16 v[84:87], v[174:177], v[210:213], v[84:87]
	v_mfma_f32_16x16x32_bf16 v[80:83], v[182:185], v[210:213], v[80:83]
	v_mfma_f32_16x16x32_bf16 v[68:71], v[174:177], v[218:221], v[68:71]
	v_mfma_f32_16x16x32_bf16 v[64:67], v[182:185], v[218:221], v[64:67]
	v_mfma_f32_16x16x32_bf16 v[116:119], v[178:181], v[194:197], v[116:119]
	v_mfma_f32_16x16x32_bf16 v[112:115], v[186:189], v[194:197], v[112:115]
	v_mfma_f32_16x16x32_bf16 v[100:103], v[178:181], v[202:205], v[100:103]
	v_mfma_f32_16x16x32_bf16 v[96:99], v[186:189], v[202:205], v[96:99]
	v_mfma_f32_16x16x32_bf16 v[84:87], v[178:181], v[214:217], v[84:87]
	v_mfma_f32_16x16x32_bf16 v[80:83], v[186:189], v[214:217], v[80:83]
	v_mfma_f32_16x16x32_bf16 v[68:71], v[178:181], v[222:225], v[68:71]
	v_mfma_f32_16x16x32_bf16 v[64:67], v[186:189], v[222:225], v[64:67]
	s_setprio 0
	s_barrier
	s_add_i32 s22, s39, s81
	v_lshl_add_u64 v[150:151], s[8:9], 0, v[130:131]
	s_mov_b32 m0, s22
	ds_read_b128 v[190:193], v157 offset:16384
	ds_read_b128 v[194:197], v157 offset:17408
	ds_read_b128 v[198:201], v157 offset:18432
	ds_read_b128 v[202:205], v157 offset:19456
	ds_read_b128 v[210:213], v157 offset:20480
	ds_read_b128 v[214:217], v157 offset:21504
	ds_read_b128 v[218:221], v157 offset:22528
	ds_read_b128 v[222:225], v157 offset:23552
	global_load_lds_dwordx4 v[150:151], off
	s_add_i32 m0, s22, 0x2000
	s_add_u32 s22, s8, 0x18000
	v_lshl_add_u64 v[206:207], s[8:9], 0, v[134:135]
	s_addc_u32 s23, s9, 0
	s_add_i32 s49, s40, s81
	global_load_lds_dwordx4 v[206:207], off
	v_lshl_add_u64 v[226:227], s[22:23], 0, v[130:131]
	s_mov_b32 m0, s49
	v_lshl_add_u64 v[228:229], s[24:25], 0, v[132:133]
	global_load_lds_dwordx4 v[226:227], off
	v_lshl_add_u64 v[226:227], s[22:23], 0, v[134:135]
	s_add_i32 m0, s49, 0x2000
	s_nop 0
	global_load_lds_dwordx4 v[226:227], off
	v_lshl_add_u64 v[226:227], s[24:25], 0, v[128:129]
	s_mov_b32 m0, s27
	s_nop 0
	global_load_lds_dwordx4 v[226:227], off
	s_mov_b32 m0, s28
	s_nop 0
	global_load_lds_dwordx4 v[228:229], off
	s_waitcnt vmcnt(8) lgkmcnt(0)
	s_barrier
; #define PG8_STAGE(bufoff, gbase, voff) do { _Pragma("unroll") for (int _i = 0; _i < 2; ++_i) \
;         __builtin_amdgcn_global_load_lds((const unsigned*)((const char*)(gbase) + (voff)[_i]), (LAS unsigned*)(lds + (bufoff) + ldsw + _i * 8192), 16, 0, 0); } while (0)
; #define PG8_LDA(dst, b, h) do { _Pragma("unroll") for (int m = 0; m < 4; ++m) _Pragma("unroll") for (int k = 0; k < 2; ++k) dst[m][k] = *(const LAS bf16x8*)(lds + PG8_SA(b, h) + aoff + m * 2048 + k * 1024); } while (0)
; #define PG8_LDB(dst, b, h) do { _Pragma("unroll") for (int n = 0; n < 2; ++n) _Pragma("unroll") for (int k = 0; k < 2; ++k) dst[n][k] = *(const LAS bf16x8*)(lds + PG8_SB(b, h) + boff + n * 2048 + k * 1024); } while (0)
; #define PG8_MMA(ai, bj, At, Bt) do { __builtin_amdgcn_s_setprio(1); _Pragma("unroll") for (int m = 0; m < 4; ++m) _Pragma("unroll") for (int n = 0; n < 2; ++n) _Pragma("unroll") for (int k = 0; k < 2; ++k) \
;         acc[ai][bj][m][n] = __builtin_amdgcn_mfma_f32_16x16x32_bf16(Bt[n][k], At[m][k], acc[ai][bj][m][n], 0, 0, 0); __builtin_amdgcn_s_setprio(0); } while (0)
; #define PG8_WAIT_V(n) asm volatile("s_waitcnt vmcnt(" #n ")" ::: "memory")
; #define PG8_WAIT_L(n) asm volatile("s_waitcnt lgkmcnt(" #n ")" ::: "memory")
; #define PG8_BAR __builtin_amdgcn_s_barrier()
; #define PG8_SCHED __builtin_amdgcn_sched_barrier(0)
; template <class Epi, class Sched>
; __device__ __forceinline__ void gemm_phase(LAS unsigned char* lds, const Gemm g, const Sched& S, const Epi& E, const int wave_s) {
;     ...
;             PG8_WAIT_V(8); PG8_WAIT_L(0); PG8_BAR; PG8_MMA(1, 0, At, B0); PG8_MMA(1, 1, At, B1); PG8_BAR; PG8_SCHED;
;             PG8_LDB(B0, 1, 0); PG8_LDB(B1, 1, 1); PG8_SCHED; PG8_LDA(At, 1, 0); PG8_STAGE(PG8_SA(0, 1), a2 + hstepA, voffA);
;             PG8_WAIT_V(8); PG8_WAIT_L(0); PG8_BAR; PG8_MMA(0, 0, At, B0); PG8_MMA(0, 1, At, B1); PG8_BAR; PG8_SCHED;
	s_setprio 1
	v_mfma_f32_16x16x32_bf16 v[60:63], v[158:161], v[190:193], v[60:63]
	v_mfma_f32_16x16x32_bf16 v[56:59], v[166:169], v[190:193], v[56:59]
	v_mfma_f32_16x16x32_bf16 v[44:47], v[158:161], v[198:201], v[44:47]
	v_mfma_f32_16x16x32_bf16 v[40:43], v[166:169], v[198:201], v[40:43]
	v_mfma_f32_16x16x32_bf16 v[28:31], v[158:161], v[210:213], v[28:31]
	v_mfma_f32_16x16x32_bf16 v[24:27], v[166:169], v[210:213], v[24:27]
	v_mfma_f32_16x16x32_bf16 v[12:15], v[158:161], v[218:221], v[12:15]
	v_mfma_f32_16x16x32_bf16 v[8:11], v[166:169], v[218:221], v[8:11]
	v_mfma_f32_16x16x32_bf16 v[60:63], v[162:165], v[194:197], v[60:63]
	v_mfma_f32_16x16x32_bf16 v[56:59], v[170:173], v[194:197], v[56:59]
	v_mfma_f32_16x16x32_bf16 v[44:47], v[162:165], v[202:205], v[44:47]
	v_mfma_f32_16x16x32_bf16 v[40:43], v[170:173], v[202:205], v[40:43]
	v_mfma_f32_16x16x32_bf16 v[28:31], v[162:165], v[214:217], v[28:31]
	v_mfma_f32_16x16x32_bf16 v[24:27], v[170:173], v[214:217], v[24:27]
	v_mfma_f32_16x16x32_bf16 v[12:15], v[162:165], v[222:225], v[12:15]
	v_mfma_f32_16x16x32_bf16 v[8:11], v[170:173], v[222:225], v[8:11]
	s_nop 0
	s_nop 0
	v_mfma_f32_16x16x32_bf16 v[52:55], v[174:177], v[190:193], v[52:55]
	v_mfma_f32_16x16x32_bf16 v[48:51], v[182:185], v[190:193], v[48:51]
	v_mfma_f32_16x16x32_bf16 v[36:39], v[174:177], v[198:201], v[36:39]
	v_mfma_f32_16x16x32_bf16 v[32:35], v[182:185], v[198:201], v[32:35]
	v_mfma_f32_16x16x32_bf16 v[20:23], v[174:177], v[210:213], v[20:23]
	v_mfma_f32_16x16x32_bf16 v[16:19], v[182:185], v[210:213], v[16:19]
	v_mfma_f32_16x16x32_bf16 v[4:7], v[174:177], v[218:221], v[4:7]
	v_mfma_f32_16x16x32_bf16 v[0:3], v[182:185], v[218:221], v[0:3]
	v_mfma_f32_16x16x32_bf16 v[52:55], v[178:181], v[194:197], v[52:55]
	v_mfma_f32_16x16x32_bf16 v[48:51], v[186:189], v[194:197], v[48:51]
	v_mfma_f32_16x16x32_bf16 v[36:39], v[178:181], v[202:205], v[36:39]
	v_mfma_f32_16x16x32_bf16 v[32:35], v[186:189], v[202:205], v[32:35]
	v_mfma_f32_16x16x32_bf16 v[20:23], v[178:181], v[214:217], v[20:23]
	v_mfma_f32_16x16x32_bf16 v[16:19], v[186:189], v[214:217], v[16:19]
	v_mfma_f32_16x16x32_bf16 v[4:7], v[178:181], v[222:225], v[4:7]
	v_mfma_f32_16x16x32_bf16 v[0:3], v[186:189], v[222:225], v[0:3]
	s_setprio 0
	s_barrier
	s_add_i32 s49, 0, 0x18000
	v_add_u32_e32 v136, s49, v153
	s_add_i32 s50, 0, 0x1c000
	ds_read_b128 v[158:161], v136
	ds_read_b128 v[162:165], v136 offset:1024
	ds_read_b128 v[166:169], v136 offset:2048
	ds_read_b128 v[170:173], v136 offset:3072
	v_add_u32_e32 v136, s50, v153
	ds_read_b128 v[174:177], v136
	ds_read_b128 v[178:181], v136 offset:1024
	ds_read_b128 v[182:185], v136 offset:2048
	ds_read_b128 v[186:189], v136 offset:3072
	s_add_u32 s22, s24, 0xf0000
	s_addc_u32 s23, s25, 0
	s_mov_b32 m0, s29
	v_lshl_add_u64 v[230:231], s[22:23], 0, v[128:129]
	ds_read_b128 v[190:193], v157 offset:32768
	ds_read_b128 v[194:197], v157 offset:33792
	ds_read_b128 v[198:201], v157 offset:34816
	ds_read_b128 v[202:205], v157 offset:35840
	ds_read_b128 v[210:213], v157 offset:36864
	ds_read_b128 v[214:217], v157 offset:37888
	ds_read_b128 v[218:221], v157 offset:38912
	ds_read_b128 v[222:225], v157 offset:39936
	global_load_lds_dwordx4 v[230:231], off
	v_lshl_add_u64 v[230:231], s[22:23], 0, v[132:133]
	s_mov_b32 m0, s30
	s_nop 0
	global_load_lds_dwordx4 v[230:231], off
	s_waitcnt vmcnt(8) lgkmcnt(0)
	s_barrier
	s_setprio 1
	v_mfma_f32_16x16x32_bf16 v[124:127], v[158:161], v[190:193], v[124:127]
	v_mfma_f32_16x16x32_bf16 v[120:123], v[166:169], v[190:193], v[120:123]
	v_mfma_f32_16x16x32_bf16 v[108:111], v[158:161], v[198:201], v[108:111]
	v_mfma_f32_16x16x32_bf16 v[104:107], v[166:169], v[198:201], v[104:107]
	v_mfma_f32_16x16x32_bf16 v[92:95], v[158:161], v[210:213], v[92:95]
	v_mfma_f32_16x16x32_bf16 v[88:91], v[166:169], v[210:213], v[88:91]
	v_mfma_f32_16x16x32_bf16 v[76:79], v[158:161], v[218:221], v[76:79]
	v_mfma_f32_16x16x32_bf16 v[72:75], v[166:169], v[218:221], v[72:75]
	v_mfma_f32_16x16x32_bf16 v[124:127], v[162:165], v[194:197], v[124:127]
	v_mfma_f32_16x16x32_bf16 v[120:123], v[170:173], v[194:197], v[120:123]
	v_mfma_f32_16x16x32_bf16 v[108:111], v[162:165], v[202:205], v[108:111]
	v_mfma_f32_16x16x32_bf16 v[104:107], v[170:173], v[202:205], v[104:107]
	v_mfma_f32_16x16x32_bf16 v[92:95], v[162:165], v[214:217], v[92:95]
	v_mfma_f32_16x16x32_bf16 v[88:91], v[170:173], v[214:217], v[88:91]
	v_mfma_f32_16x16x32_bf16 v[76:79], v[162:165], v[222:225], v[76:79]
	v_mfma_f32_16x16x32_bf16 v[72:75], v[170:173], v[222:225], v[72:75]
	s_nop 0
	s_nop 0
	v_mfma_f32_16x16x32_bf16 v[116:119], v[174:177], v[190:193], v[116:119]
	v_mfma_f32_16x16x32_bf16 v[112:115], v[182:185], v[190:193], v[112:115]
	v_mfma_f32_16x16x32_bf16 v[100:103], v[174:177], v[198:201], v[100:103]
	v_mfma_f32_16x16x32_bf16 v[96:99], v[182:185], v[198:201], v[96:99]
	v_mfma_f32_16x16x32_bf16 v[84:87], v[174:177], v[210:213], v[84:87]
	v_mfma_f32_16x16x32_bf16 v[80:83], v[182:185], v[210:213], v[80:83]
	v_mfma_f32_16x16x32_bf16 v[68:71], v[174:177], v[218:221], v[68:71]
	v_mfma_f32_16x16x32_bf16 v[64:67], v[182:185], v[218:221], v[64:67]
	v_mfma_f32_16x16x32_bf16 v[116:119], v[178:181], v[194:197], v[116:119]
	v_mfma_f32_16x16x32_bf16 v[112:115], v[186:189], v[194:197], v[112:115]
	v_mfma_f32_16x16x32_bf16 v[100:103], v[178:181], v[202:205], v[100:103]
	v_mfma_f32_16x16x32_bf16 v[96:99], v[186:189], v[202:205], v[96:99]
	v_mfma_f32_16x16x32_bf16 v[84:87], v[178:181], v[214:217], v[84:87]
	v_mfma_f32_16x16x32_bf16 v[80:83], v[186:189], v[214:217], v[80:83]
	v_mfma_f32_16x16x32_bf16 v[68:71], v[178:181], v[222:225], v[68:71]
	v_mfma_f32_16x16x32_bf16 v[64:67], v[186:189], v[222:225], v[64:67]
	s_setprio 0
	s_barrier
; #define PG8_STAGE(bufoff, gbase, voff) do { _Pragma("unroll") for (int _i = 0; _i < 2; ++_i) \
;         __builtin_amdgcn_global_load_lds((const unsigned*)((const char*)(gbase) + (voff)[_i]), (LAS unsigned*)(lds + (bufoff) + ldsw + _i * 8192), 16, 0, 0); } while (0)
; #define PG8_LDA(dst, b, h) do { _Pragma("unroll") for (int m = 0; m < 4; ++m) _Pragma("unroll") for (int k = 0; k < 2; ++k) dst[m][k] = *(const LAS bf16x8*)(lds + PG8_SA(b, h) + aoff + m * 2048 + k * 1024); } while (0)
; #define PG8_MMA(ai, bj, At, Bt) do { __builtin_amdgcn_s_setprio(1); _Pragma("unroll") for (int m = 0; m < 4; ++m) _Pragma("unroll") for (int n = 0; n < 2; ++n) _Pragma("unroll") for (int k = 0; k < 2; ++k) \
;         acc[ai][bj][m][n] = __builtin_amdgcn_mfma_f32_16x16x32_bf16(Bt[n][k], At[m][k], acc[ai][bj][m][n], 0, 0, 0); __builtin_amdgcn_s_setprio(0); } while (0)
; #define PG8_WAIT_V(n) asm volatile("s_waitcnt vmcnt(" #n ")" ::: "memory")
; #define PG8_WAIT_L(n) asm volatile("s_waitcnt lgkmcnt(" #n ")" ::: "memory")
; #define PG8_BAR __builtin_amdgcn_s_barrier()
; #define PG8_SCHED __builtin_amdgcn_sched_barrier(0)
; template <class Epi, class Sched>
; __device__ __forceinline__ void gemm_phase(LAS unsigned char* lds, const Gemm g, const Sched& S, const Epi& E, const int wave_s) {
;     ...
;             PG8_LDA(At, 1, 1); PG8_STAGE(PG8_SB(1, 0), b3, voffB); PG8_STAGE(PG8_SB(1, 1), b3 + hstepB, voffB); PG8_STAGE(PG8_SA(1, 0), a3, voffA);
;             PG8_WAIT_V(8); PG8_WAIT_L(0); PG8_BAR; PG8_MMA(1, 0, At, B0); PG8_MMA(1, 1, At, B1); PG8_BAR; PG8_SCHED;
;         }
;         if (wr == 0) PG8_BAR;
	s_add_i32 s22, s49, s81
	v_lshl_add_u64 v[150:151], v[150:151], 0, s[14:15]
	s_mov_b32 m0, s22
	ds_read_b128 v[190:193], v157 offset:49152
	ds_read_b128 v[194:197], v157 offset:50176
	ds_read_b128 v[198:201], v157 offset:51200
	ds_read_b128 v[202:205], v157 offset:52224
	ds_read_b128 v[210:213], v157 offset:53248
	ds_read_b128 v[214:217], v157 offset:54272
	ds_read_b128 v[218:221], v157 offset:55296
	ds_read_b128 v[222:225], v157 offset:56320
	global_load_lds_dwordx4 v[150:151], off
	s_add_i32 m0, s22, 0x2000
	s_add_u32 s8, s8, 0x18080
	v_lshl_add_u64 v[150:151], v[206:207], 0, s[14:15]
	s_addc_u32 s9, s9, 0
	s_add_i32 s22, s50, s81
	global_load_lds_dwordx4 v[150:151], off
	v_lshl_add_u64 v[150:151], s[8:9], 0, v[130:131]
	s_mov_b32 m0, s22
	s_nop 0
	global_load_lds_dwordx4 v[150:151], off
	v_lshl_add_u64 v[150:151], s[8:9], 0, v[134:135]
	s_add_i32 m0, s22, 0x2000
	s_nop 0
	global_load_lds_dwordx4 v[150:151], off
	v_lshl_add_u64 v[150:151], v[226:227], 0, s[14:15]
	s_mov_b32 m0, s33
	s_nop 0
	global_load_lds_dwordx4 v[150:151], off
	v_lshl_add_u64 v[150:151], v[228:229], 0, s[14:15]
	s_mov_b32 m0, s34
	s_nop 0
	global_load_lds_dwordx4 v[150:151], off
	s_waitcnt vmcnt(8) lgkmcnt(0)
	s_barrier
	s_setprio 1
	v_mfma_f32_16x16x32_bf16 v[60:63], v[158:161], v[190:193], v[60:63]
	v_mfma_f32_16x16x32_bf16 v[56:59], v[166:169], v[190:193], v[56:59]
	v_mfma_f32_16x16x32_bf16 v[44:47], v[158:161], v[198:201], v[44:47]
	v_mfma_f32_16x16x32_bf16 v[40:43], v[166:169], v[198:201], v[40:43]
	v_mfma_f32_16x16x32_bf16 v[28:31], v[158:161], v[210:213], v[28:31]
	v_mfma_f32_16x16x32_bf16 v[24:27], v[166:169], v[210:213], v[24:27]
	v_mfma_f32_16x16x32_bf16 v[12:15], v[158:161], v[218:221], v[12:15]
	v_mfma_f32_16x16x32_bf16 v[8:11], v[166:169], v[218:221], v[8:11]
	v_mfma_f32_16x16x32_bf16 v[60:63], v[162:165], v[194:197], v[60:63]
	v_mfma_f32_16x16x32_bf16 v[56:59], v[170:173], v[194:197], v[56:59]
	v_mfma_f32_16x16x32_bf16 v[44:47], v[162:165], v[202:205], v[44:47]
	v_mfma_f32_16x16x32_bf16 v[40:43], v[170:173], v[202:205], v[40:43]
	v_mfma_f32_16x16x32_bf16 v[28:31], v[162:165], v[214:217], v[28:31]
	v_mfma_f32_16x16x32_bf16 v[24:27], v[170:173], v[214:217], v[24:27]
	v_mfma_f32_16x16x32_bf16 v[12:15], v[162:165], v[222:225], v[12:15]
	v_mfma_f32_16x16x32_bf16 v[8:11], v[170:173], v[222:225], v[8:11]
	s_nop 0
	s_nop 0
	v_mfma_f32_16x16x32_bf16 v[52:55], v[174:177], v[190:193], v[52:55]
	v_mfma_f32_16x16x32_bf16 v[48:51], v[182:185], v[190:193], v[48:51]
	v_mfma_f32_16x16x32_bf16 v[36:39], v[174:177], v[198:201], v[36:39]
	v_mfma_f32_16x16x32_bf16 v[32:35], v[182:185], v[198:201], v[32:35]
	v_mfma_f32_16x16x32_bf16 v[20:23], v[174:177], v[210:213], v[20:23]
	v_mfma_f32_16x16x32_bf16 v[16:19], v[182:185], v[210:213], v[16:19]
	v_mfma_f32_16x16x32_bf16 v[4:7], v[174:177], v[218:221], v[4:7]
	v_mfma_f32_16x16x32_bf16 v[0:3], v[182:185], v[218:221], v[0:3]
	v_mfma_f32_16x16x32_bf16 v[52:55], v[178:181], v[194:197], v[52:55]
	v_mfma_f32_16x16x32_bf16 v[48:51], v[186:189], v[194:197], v[48:51]
	v_mfma_f32_16x16x32_bf16 v[36:39], v[178:181], v[202:205], v[36:39]
	v_mfma_f32_16x16x32_bf16 v[32:35], v[186:189], v[202:205], v[32:35]
	v_mfma_f32_16x16x32_bf16 v[20:23], v[178:181], v[214:217], v[20:23]
	v_mfma_f32_16x16x32_bf16 v[16:19], v[186:189], v[214:217], v[16:19]
	v_mfma_f32_16x16x32_bf16 v[4:7], v[178:181], v[222:225], v[4:7]
	v_mfma_f32_16x16x32_bf16 v[0:3], v[186:189], v[222:225], v[0:3]
	s_setprio 0
	s_barrier
	s_add_i32 s48, s48, 2
	s_add_u32 s46, s46, 0x100
	s_addc_u32 s47, s47, 0
	s_cmp_gt_u32 s48, 3
	s_mov_b64 s[22:23], s[4:5]
	s_cbranch_scc0 .LBB0_375
	s_and_b64 vcc, exec, s[16:17]
	s_cbranch_vccz .LBB0_378
	s_barrier

; #define PG8_STAGE(bufoff, gbase, voff) do { _Pragma("unroll") for (int _i = 0; _i < 2; ++_i) \
;         __builtin_amdgcn_global_load_lds((const unsigned*)((const char*)(gbase) + (voff)[_i]), (LAS unsigned*)(lds + (bufoff) + ldsw + _i * 8192), 16, 0, 0); } while (0)
; #define PG8_LDA(dst, b, h) do { _Pragma("unroll") for (int m = 0; m < 4; ++m) _Pragma("unroll") for (int k = 0; k < 2; ++k) dst[m][k] = *(const LAS bf16x8*)(lds + PG8_SA(b, h) + aoff + m * 2048 + k * 1024); } while (0)
; #define PG8_LDB(dst, b, h) do { _Pragma("unroll") for (int n = 0; n < 2; ++n) _Pragma("unroll") for (int k = 0; k < 2; ++k) dst[n][k] = *(const LAS bf16x8*)(lds + PG8_SB(b, h) + boff + n * 2048 + k * 1024); } while (0)
; #define PG8_MMA(ai, bj, At, Bt) do { __builtin_amdgcn_s_setprio(1); _Pragma("unroll") for (int m = 0; m < 4; ++m) _Pragma("unroll") for (int n = 0; n < 2; ++n) _Pragma("unroll") for (int k = 0; k < 2; ++k) \
;         acc[ai][bj][m][n] = __builtin_amdgcn_mfma_f32_16x16x32_bf16(Bt[n][k], At[m][k], acc[ai][bj][m][n], 0, 0, 0); __builtin_amdgcn_s_setprio(0); } while (0)
; #define PG8_BAR __builtin_amdgcn_s_barrier()
; template <class Epi, class Sched>
; __device__ __forceinline__ void gemm_phase(LAS unsigned char* lds, const Gemm g, const Sched& S, const Epi& E, const int wave_s) {
;     ...
;         const char* nA = has_next ? (const char*)g.A + (size_t)nxt.pm * tstepA + (size_t)nxt.acol * 2 : cA; const char* nB = has_next ? (const char*)g.Bt + (size_t)nxt.pn * tstepB : cB;
; #pragma unroll 1
;         for (int t = 0; t < nt; t += 2) {
;             const bool last = (t == nt - 2);
;             const char* a1 = cA + (size_t)(t + 1) * kstep;
;             const char* a2 = last ? nA : cA + (size_t)(t + 2) * kstep; const char* b2 = last ? nB : cB + (size_t)(t + 2) * kstep;
;             const char* a3 = a2 + kstep; const char* b3 = b2 + kstep;
;             PG8_LDB(B0, 0, 0); PG8_LDB(B1, 0, 1); PG8_SCHED; PG8_LDA(At, 0, 0); PG8_STAGE(PG8_SA(1, 1), a1 + hstepA, voffA);
;             PG8_WAIT_V(8); PG8_WAIT_L(0); PG8_BAR; PG8_MMA(0, 0, At, B0); PG8_MMA(0, 1, At, B1); PG8_BAR; PG8_SCHED;
;             PG8_LDA(At, 0, 1); PG8_STAGE(PG8_SB(0, 0), b2, voffB); PG8_STAGE(PG8_SB(0, 1), b2 + hstepB, voffB); PG8_STAGE(PG8_SA(0, 0), a2, voffA);
;             PG8_WAIT_V(8); PG8_WAIT_L(0); PG8_BAR; PG8_MMA(1, 0, At, B0); PG8_MMA(1, 1, At, B1); PG8_BAR; PG8_SCHED;
.LBB0_417:
	s_add_u32 s39, s36, s38
	s_addc_u32 s44, s37, 0
	s_add_u32 s42, s39, 0x100
	s_addc_u32 s43, s44, 0
	s_and_b64 s[40:41], s[4:5], exec
	s_cselect_b32 s41, s29, s43
	s_cselect_b32 s40, s28, s42
	s_add_u32 s38, s34, s38
	s_addc_u32 s42, s35, 0
	s_add_u32 s38, s38, 0x100
	s_addc_u32 s42, s42, 0
	s_and_b64 s[4:5], s[4:5], exec
	s_cselect_b32 s43, s27, s42
	s_cselect_b32 s42, s68, s38
	s_add_u32 s46, s39, 0xf0080
	ds_read_b128 v[148:151], v145
	ds_read_b128 v[152:155], v145 offset:1024
	ds_read_b128 v[156:159], v145 offset:2048
	ds_read_b128 v[160:163], v145 offset:3072
	ds_read_b128 v[164:167], v146
	ds_read_b128 v[168:171], v146 offset:1024
	ds_read_b128 v[172:175], v146 offset:2048
	ds_read_b128 v[176:179], v146 offset:3072
	s_addc_u32 s47, s44, 0
	s_add_i32 s76, s59, s81
	s_add_i32 m0, s49, 0xc000
	s_add_i32 s79, s49, 0xe000
	s_add_i32 s73, s76, 0x2000
	s_add_u32 s44, s42, 0x10000
	s_addc_u32 s45, s43, 0
	s_add_i32 s75, s60, s81
	s_add_i32 s74, s75, 0x2000
	s_add_i32 s72, 0, 0x18000
	s_add_i32 s71, 0, 0x1c000
	s_add_u32 s38, s40, 0xf0000
	s_addc_u32 s39, s41, 0
	s_add_i32 s70, s72, s81
	s_add_i32 s69, s70, 0x2000
	s_add_u32 s4, s42, 0x10080
	s_addc_u32 s5, s43, 0
	s_add_i32 s78, s71, s81
	s_add_i32 s77, s78, 0x2000
	v_lshl_add_u64 v[140:141], s[46:47], 0, v[128:129]
	ds_read_b128 v[180:183], v147
	ds_read_b128 v[184:187], v147 offset:1024
	ds_read_b128 v[188:191], v147 offset:2048
	ds_read_b128 v[192:195], v147 offset:3072
	ds_read_b128 v[196:199], v147 offset:4096
	ds_read_b128 v[200:203], v147 offset:5120
	ds_read_b128 v[204:207], v147 offset:6144
	ds_read_b128 v[210:213], v147 offset:7168
	global_load_lds_dwordx4 v[140:141], off
	v_lshl_add_u64 v[140:141], s[46:47], 0, v[132:133]
	s_mov_b32 m0, s79
	s_nop 0
	global_load_lds_dwordx4 v[140:141], off
	s_waitcnt vmcnt(8) lgkmcnt(0)
	s_barrier
	s_setprio 1
	v_mfma_f32_16x16x32_bf16 v[124:127], v[148:151], v[180:183], v[124:127]
	v_mfma_f32_16x16x32_bf16 v[120:123], v[156:159], v[180:183], v[120:123]
	v_mfma_f32_16x16x32_bf16 v[116:119], v[148:151], v[188:191], v[116:119]
	v_mfma_f32_16x16x32_bf16 v[108:111], v[156:159], v[188:191], v[108:111]
	v_mfma_f32_16x16x32_bf16 v[100:103], v[148:151], v[196:199], v[100:103]
	v_mfma_f32_16x16x32_bf16 v[92:95], v[156:159], v[196:199], v[92:95]
	v_mfma_f32_16x16x32_bf16 v[84:87], v[148:151], v[204:207], v[84:87]
	v_mfma_f32_16x16x32_bf16 v[76:79], v[156:159], v[204:207], v[76:79]
	v_mfma_f32_16x16x32_bf16 v[124:127], v[152:155], v[184:187], v[124:127]
	v_mfma_f32_16x16x32_bf16 v[120:123], v[160:163], v[184:187], v[120:123]
	v_mfma_f32_16x16x32_bf16 v[116:119], v[152:155], v[192:195], v[116:119]
	v_mfma_f32_16x16x32_bf16 v[108:111], v[160:163], v[192:195], v[108:111]
	v_mfma_f32_16x16x32_bf16 v[100:103], v[152:155], v[200:203], v[100:103]
	v_mfma_f32_16x16x32_bf16 v[92:95], v[160:163], v[200:203], v[92:95]
	v_mfma_f32_16x16x32_bf16 v[84:87], v[152:155], v[210:213], v[84:87]
	v_mfma_f32_16x16x32_bf16 v[76:79], v[160:163], v[210:213], v[76:79]
	s_nop 0
	s_nop 0
	v_mfma_f32_16x16x32_bf16 v[112:115], v[164:167], v[180:183], v[112:115]
	v_mfma_f32_16x16x32_bf16 v[104:107], v[172:175], v[180:183], v[104:107]
	v_mfma_f32_16x16x32_bf16 v[96:99], v[164:167], v[188:191], v[96:99]
	v_mfma_f32_16x16x32_bf16 v[88:91], v[172:175], v[188:191], v[88:91]
	v_mfma_f32_16x16x32_bf16 v[80:83], v[164:167], v[196:199], v[80:83]
	v_mfma_f32_16x16x32_bf16 v[72:75], v[172:175], v[196:199], v[72:75]
	v_mfma_f32_16x16x32_bf16 v[68:71], v[164:167], v[204:207], v[68:71]
	v_mfma_f32_16x16x32_bf16 v[64:67], v[172:175], v[204:207], v[64:67]
	v_mfma_f32_16x16x32_bf16 v[112:115], v[168:171], v[184:187], v[112:115]
	v_mfma_f32_16x16x32_bf16 v[104:107], v[176:179], v[184:187], v[104:107]
	v_mfma_f32_16x16x32_bf16 v[96:99], v[168:171], v[192:195], v[96:99]
	v_mfma_f32_16x16x32_bf16 v[88:91], v[176:179], v[192:195], v[88:91]
	v_mfma_f32_16x16x32_bf16 v[80:83], v[168:171], v[200:203], v[80:83]
	v_mfma_f32_16x16x32_bf16 v[72:75], v[176:179], v[200:203], v[72:75]
	v_mfma_f32_16x16x32_bf16 v[68:71], v[168:171], v[210:213], v[68:71]
	v_mfma_f32_16x16x32_bf16 v[64:67], v[176:179], v[210:213], v[64:67]
	s_setprio 0
	s_barrier
	s_mov_b32 m0, s76
	v_lshl_add_u64 v[140:141], s[42:43], 0, v[130:131]
	ds_read_b128 v[180:183], v147 offset:16384
	ds_read_b128 v[184:187], v147 offset:17408
	ds_read_b128 v[188:191], v147 offset:18432
	ds_read_b128 v[192:195], v147 offset:19456
	ds_read_b128 v[196:199], v147 offset:20480
	ds_read_b128 v[200:203], v147 offset:21504
	ds_read_b128 v[204:207], v147 offset:22528
	ds_read_b128 v[210:213], v147 offset:23552
	global_load_lds_dwordx4 v[140:141], off
	v_lshl_add_u64 v[214:215], s[42:43], 0, v[134:135]
	s_mov_b32 m0, s73
	v_lshl_add_u64 v[216:217], s[44:45], 0, v[130:131]
	global_load_lds_dwordx4 v[214:215], off
	s_mov_b32 m0, s75
	v_lshl_add_u64 v[218:219], s[40:41], 0, v[132:133]
	global_load_lds_dwordx4 v[216:217], off
	v_lshl_add_u64 v[216:217], s[44:45], 0, v[134:135]
	s_mov_b32 m0, s74
	s_nop 0
	global_load_lds_dwordx4 v[216:217], off
	v_lshl_add_u64 v[216:217], s[40:41], 0, v[128:129]
	s_mov_b32 m0, s49
	s_nop 0
	global_load_lds_dwordx4 v[216:217], off
	s_mov_b32 m0, s50
	s_nop 0
	global_load_lds_dwordx4 v[218:219], off
	s_waitcnt vmcnt(8) lgkmcnt(0)
	s_barrier
; #define PG8_STAGE(bufoff, gbase, voff) do { _Pragma("unroll") for (int _i = 0; _i < 2; ++_i) \
;         __builtin_amdgcn_global_load_lds((const unsigned*)((const char*)(gbase) + (voff)[_i]), (LAS unsigned*)(lds + (bufoff) + ldsw + _i * 8192), 16, 0, 0); } while (0)
; #define PG8_LDA(dst, b, h) do { _Pragma("unroll") for (int m = 0; m < 4; ++m) _Pragma("unroll") for (int k = 0; k < 2; ++k) dst[m][k] = *(const LAS bf16x8*)(lds + PG8_SA(b, h) + aoff + m * 2048 + k * 1024); } while (0)
; #define PG8_LDB(dst, b, h) do { _Pragma("unroll") for (int n = 0; n < 2; ++n) _Pragma("unroll") for (int k = 0; k < 2; ++k) dst[n][k] = *(const LAS bf16x8*)(lds + PG8_SB(b, h) + boff + n * 2048 + k * 1024); } while (0)
; #define PG8_MMA(ai, bj, At, Bt) do { __builtin_amdgcn_s_setprio(1); _Pragma("unroll") for (int m = 0; m < 4; ++m) _Pragma("unroll") for (int n = 0; n < 2; ++n) _Pragma("unroll") for (int k = 0; k < 2; ++k) \
;         acc[ai][bj][m][n] = __builtin_amdgcn_mfma_f32_16x16x32_bf16(Bt[n][k], At[m][k], acc[ai][bj][m][n], 0, 0, 0); __builtin_amdgcn_s_setprio(0); } while (0)
; #define PG8_WAIT_V(n) asm volatile("s_waitcnt vmcnt(" #n ")" ::: "memory")
; #define PG8_WAIT_L(n) asm volatile("s_waitcnt lgkmcnt(" #n ")" ::: "memory")
; #define PG8_BAR __builtin_amdgcn_s_barrier()
; #define PG8_SCHED __builtin_amdgcn_sched_barrier(0)
; template <class Epi, class Sched>
; __device__ __forceinline__ void gemm_phase(LAS unsigned char* lds, const Gemm g, const Sched& S, const Epi& E, const int wave_s) {
;     ...
;             PG8_WAIT_V(8); PG8_WAIT_L(0); PG8_BAR; PG8_MMA(1, 0, At, B0); PG8_MMA(1, 1, At, B1); PG8_BAR; PG8_SCHED;
;             PG8_LDB(B0, 1, 0); PG8_LDB(B1, 1, 1); PG8_SCHED; PG8_LDA(At, 1, 0); PG8_STAGE(PG8_SA(0, 1), a2 + hstepA, voffA);
;             PG8_WAIT_V(8); PG8_WAIT_L(0); PG8_BAR; PG8_MMA(0, 0, At, B0); PG8_MMA(0, 1, At, B1); PG8_BAR; PG8_SCHED;
	s_setprio 1
	v_mfma_f32_16x16x32_bf16 v[60:63], v[148:151], v[180:183], v[60:63]
	v_mfma_f32_16x16x32_bf16 v[56:59], v[156:159], v[180:183], v[56:59]
	v_mfma_f32_16x16x32_bf16 v[52:55], v[148:151], v[188:191], v[52:55]
	v_mfma_f32_16x16x32_bf16 v[44:47], v[156:159], v[188:191], v[44:47]
	v_mfma_f32_16x16x32_bf16 v[36:39], v[148:151], v[196:199], v[36:39]
	v_mfma_f32_16x16x32_bf16 v[28:31], v[156:159], v[196:199], v[28:31]
	v_mfma_f32_16x16x32_bf16 v[20:23], v[148:151], v[204:207], v[20:23]
	v_mfma_f32_16x16x32_bf16 v[12:15], v[156:159], v[204:207], v[12:15]
	v_mfma_f32_16x16x32_bf16 v[60:63], v[152:155], v[184:187], v[60:63]
	v_mfma_f32_16x16x32_bf16 v[56:59], v[160:163], v[184:187], v[56:59]
	v_mfma_f32_16x16x32_bf16 v[52:55], v[152:155], v[192:195], v[52:55]
	v_mfma_f32_16x16x32_bf16 v[44:47], v[160:163], v[192:195], v[44:47]
	v_mfma_f32_16x16x32_bf16 v[36:39], v[152:155], v[200:203], v[36:39]
	v_mfma_f32_16x16x32_bf16 v[28:31], v[160:163], v[200:203], v[28:31]
	v_mfma_f32_16x16x32_bf16 v[20:23], v[152:155], v[210:213], v[20:23]
	v_mfma_f32_16x16x32_bf16 v[12:15], v[160:163], v[210:213], v[12:15]
	s_nop 0
	s_nop 0
	v_mfma_f32_16x16x32_bf16 v[48:51], v[164:167], v[180:183], v[48:51]
	v_mfma_f32_16x16x32_bf16 v[40:43], v[172:175], v[180:183], v[40:43]
	v_mfma_f32_16x16x32_bf16 v[32:35], v[164:167], v[188:191], v[32:35]
	v_mfma_f32_16x16x32_bf16 v[24:27], v[172:175], v[188:191], v[24:27]
	v_mfma_f32_16x16x32_bf16 v[16:19], v[164:167], v[196:199], v[16:19]
	v_mfma_f32_16x16x32_bf16 v[8:11], v[172:175], v[196:199], v[8:11]
	v_mfma_f32_16x16x32_bf16 v[4:7], v[164:167], v[204:207], v[4:7]
	v_mfma_f32_16x16x32_bf16 v[0:3], v[172:175], v[204:207], v[0:3]
	v_mfma_f32_16x16x32_bf16 v[48:51], v[168:171], v[184:187], v[48:51]
	v_mfma_f32_16x16x32_bf16 v[40:43], v[176:179], v[184:187], v[40:43]
	v_mfma_f32_16x16x32_bf16 v[32:35], v[168:171], v[192:195], v[32:35]
	v_mfma_f32_16x16x32_bf16 v[24:27], v[176:179], v[192:195], v[24:27]
	v_mfma_f32_16x16x32_bf16 v[16:19], v[168:171], v[200:203], v[16:19]
	v_mfma_f32_16x16x32_bf16 v[8:11], v[176:179], v[200:203], v[8:11]
	v_mfma_f32_16x16x32_bf16 v[4:7], v[168:171], v[210:213], v[4:7]
	v_mfma_f32_16x16x32_bf16 v[0:3], v[176:179], v[210:213], v[0:3]
	s_setprio 0
	s_barrier
	v_add_u32_e32 v160, s72, v143
	v_add_u32_e32 v176, s71, v143
	ds_read_b128 v[148:151], v160
	ds_read_b128 v[152:155], v160 offset:1024
	ds_read_b128 v[156:159], v160 offset:2048
	ds_read_b128 v[160:163], v160 offset:3072
	ds_read_b128 v[164:167], v176
	ds_read_b128 v[168:171], v176 offset:1024
	ds_read_b128 v[172:175], v176 offset:2048
	ds_read_b128 v[176:179], v176 offset:3072
	s_mov_b32 m0, s51
	v_lshl_add_u64 v[220:221], s[38:39], 0, v[128:129]
	ds_read_b128 v[180:183], v147 offset:32768
	ds_read_b128 v[184:187], v147 offset:33792
	ds_read_b128 v[188:191], v147 offset:34816
	ds_read_b128 v[192:195], v147 offset:35840
	ds_read_b128 v[196:199], v147 offset:36864
	ds_read_b128 v[200:203], v147 offset:37888
	ds_read_b128 v[204:207], v147 offset:38912
	ds_read_b128 v[210:213], v147 offset:39936
	global_load_lds_dwordx4 v[220:221], off
	v_lshl_add_u64 v[220:221], s[38:39], 0, v[132:133]
	s_mov_b32 m0, s52
	s_nop 0
	global_load_lds_dwordx4 v[220:221], off
	s_waitcnt vmcnt(8) lgkmcnt(0)
	s_barrier
	s_setprio 1
	v_mfma_f32_16x16x32_bf16 v[124:127], v[148:151], v[180:183], v[124:127]
	v_mfma_f32_16x16x32_bf16 v[120:123], v[156:159], v[180:183], v[120:123]
	v_mfma_f32_16x16x32_bf16 v[116:119], v[148:151], v[188:191], v[116:119]
	v_mfma_f32_16x16x32_bf16 v[108:111], v[156:159], v[188:191], v[108:111]
	v_mfma_f32_16x16x32_bf16 v[100:103], v[148:151], v[196:199], v[100:103]
	v_mfma_f32_16x16x32_bf16 v[92:95], v[156:159], v[196:199], v[92:95]
	v_mfma_f32_16x16x32_bf16 v[84:87], v[148:151], v[204:207], v[84:87]
	v_mfma_f32_16x16x32_bf16 v[76:79], v[156:159], v[204:207], v[76:79]
	v_mfma_f32_16x16x32_bf16 v[124:127], v[152:155], v[184:187], v[124:127]
	v_mfma_f32_16x16x32_bf16 v[120:123], v[160:163], v[184:187], v[120:123]
	v_mfma_f32_16x16x32_bf16 v[116:119], v[152:155], v[192:195], v[116:119]
	v_mfma_f32_16x16x32_bf16 v[108:111], v[160:163], v[192:195], v[108:111]
	v_mfma_f32_16x16x32_bf16 v[100:103], v[152:155], v[200:203], v[100:103]
	v_mfma_f32_16x16x32_bf16 v[92:95], v[160:163], v[200:203], v[92:95]
	v_mfma_f32_16x16x32_bf16 v[84:87], v[152:155], v[210:213], v[84:87]
	v_mfma_f32_16x16x32_bf16 v[76:79], v[160:163], v[210:213], v[76:79]
	s_nop 0
	s_nop 0
	v_mfma_f32_16x16x32_bf16 v[112:115], v[164:167], v[180:183], v[112:115]
	v_mfma_f32_16x16x32_bf16 v[104:107], v[172:175], v[180:183], v[104:107]
	v_mfma_f32_16x16x32_bf16 v[96:99], v[164:167], v[188:191], v[96:99]
	v_mfma_f32_16x16x32_bf16 v[88:91], v[172:175], v[188:191], v[88:91]
	v_mfma_f32_16x16x32_bf16 v[80:83], v[164:167], v[196:199], v[80:83]
	v_mfma_f32_16x16x32_bf16 v[72:75], v[172:175], v[196:199], v[72:75]
	v_mfma_f32_16x16x32_bf16 v[68:71], v[164:167], v[204:207], v[68:71]
	v_mfma_f32_16x16x32_bf16 v[64:67], v[172:175], v[204:207], v[64:67]
	v_mfma_f32_16x16x32_bf16 v[112:115], v[168:171], v[184:187], v[112:115]
	v_mfma_f32_16x16x32_bf16 v[104:107], v[176:179], v[184:187], v[104:107]
	v_mfma_f32_16x16x32_bf16 v[96:99], v[168:171], v[192:195], v[96:99]
	v_mfma_f32_16x16x32_bf16 v[88:91], v[176:179], v[192:195], v[88:91]
	v_mfma_f32_16x16x32_bf16 v[80:83], v[168:171], v[200:203], v[80:83]
	v_mfma_f32_16x16x32_bf16 v[72:75], v[176:179], v[200:203], v[72:75]
	v_mfma_f32_16x16x32_bf16 v[68:71], v[168:171], v[210:213], v[68:71]
	v_mfma_f32_16x16x32_bf16 v[64:67], v[176:179], v[210:213], v[64:67]
	s_setprio 0
	s_barrier
; #define PG8_STAGE(bufoff, gbase, voff) do { _Pragma("unroll") for (int _i = 0; _i < 2; ++_i) \
;         __builtin_amdgcn_global_load_lds((const unsigned*)((const char*)(gbase) + (voff)[_i]), (LAS unsigned*)(lds + (bufoff) + ldsw + _i * 8192), 16, 0, 0); } while (0)
; #define PG8_LDA(dst, b, h) do { _Pragma("unroll") for (int m = 0; m < 4; ++m) _Pragma("unroll") for (int k = 0; k < 2; ++k) dst[m][k] = *(const LAS bf16x8*)(lds + PG8_SA(b, h) + aoff + m * 2048 + k * 1024); } while (0)
; #define PG8_MMA(ai, bj, At, Bt) do { __builtin_amdgcn_s_setprio(1); _Pragma("unroll") for (int m = 0; m < 4; ++m) _Pragma("unroll") for (int n = 0; n < 2; ++n) _Pragma("unroll") for (int k = 0; k < 2; ++k) \
;         acc[ai][bj][m][n] = __builtin_amdgcn_mfma_f32_16x16x32_bf16(Bt[n][k], At[m][k], acc[ai][bj][m][n], 0, 0, 0); __builtin_amdgcn_s_setprio(0); } while (0)
; #define PG8_WAIT_V(n) asm volatile("s_waitcnt vmcnt(" #n ")" ::: "memory")
; #define PG8_WAIT_L(n) asm volatile("s_waitcnt lgkmcnt(" #n ")" ::: "memory")
; #define PG8_BAR __builtin_amdgcn_s_barrier()
; #define PG8_SCHED __builtin_amdgcn_sched_barrier(0)
; template <class Epi, class Sched>
; __device__ __forceinline__ void gemm_phase(LAS unsigned char* lds, const Gemm g, const Sched& S, const Epi& E, const int wave_s) {
;     ...
;             PG8_LDA(At, 1, 1); PG8_STAGE(PG8_SB(1, 0), b3, voffB); PG8_STAGE(PG8_SB(1, 1), b3 + hstepB, voffB); PG8_STAGE(PG8_SA(1, 0), a3, voffA);
;             PG8_WAIT_V(8); PG8_WAIT_L(0); PG8_BAR; PG8_MMA(1, 0, At, B0); PG8_MMA(1, 1, At, B1); PG8_BAR; PG8_SCHED;
;         }
;         if (wr == 0) PG8_BAR;
	s_mov_b32 m0, s70
	v_lshl_add_u64 v[140:141], v[140:141], 0, s[14:15]
	ds_read_b128 v[180:183], v147 offset:49152
	ds_read_b128 v[184:187], v147 offset:50176
	ds_read_b128 v[188:191], v147 offset:51200
	ds_read_b128 v[192:195], v147 offset:52224
	ds_read_b128 v[196:199], v147 offset:53248
	ds_read_b128 v[200:203], v147 offset:54272
	ds_read_b128 v[204:207], v147 offset:55296
	ds_read_b128 v[210:213], v147 offset:56320
	global_load_lds_dwordx4 v[140:141], off
	v_lshl_add_u64 v[140:141], v[214:215], 0, s[14:15]
	s_mov_b32 m0, s69
	s_nop 0
	global_load_lds_dwordx4 v[140:141], off
	v_lshl_add_u64 v[140:141], s[4:5], 0, v[130:131]
	s_mov_b32 m0, s78
	s_nop 0
	global_load_lds_dwordx4 v[140:141], off
	v_lshl_add_u64 v[140:141], s[4:5], 0, v[134:135]
	s_mov_b32 m0, s77
	s_nop 0
	global_load_lds_dwordx4 v[140:141], off
	v_lshl_add_u64 v[140:141], v[216:217], 0, s[14:15]
	s_mov_b32 m0, s54
	s_nop 0
	global_load_lds_dwordx4 v[140:141], off
	v_lshl_add_u64 v[140:141], v[218:219], 0, s[14:15]
	s_mov_b32 m0, s55
	s_nop 0
	global_load_lds_dwordx4 v[140:141], off
	s_waitcnt vmcnt(8) lgkmcnt(0)
	s_barrier
	s_setprio 1
	v_mfma_f32_16x16x32_bf16 v[60:63], v[148:151], v[180:183], v[60:63]
	v_mfma_f32_16x16x32_bf16 v[56:59], v[156:159], v[180:183], v[56:59]
	v_mfma_f32_16x16x32_bf16 v[52:55], v[148:151], v[188:191], v[52:55]
	v_mfma_f32_16x16x32_bf16 v[44:47], v[156:159], v[188:191], v[44:47]
	v_mfma_f32_16x16x32_bf16 v[36:39], v[148:151], v[196:199], v[36:39]
	v_mfma_f32_16x16x32_bf16 v[28:31], v[156:159], v[196:199], v[28:31]
	v_mfma_f32_16x16x32_bf16 v[20:23], v[148:151], v[204:207], v[20:23]
	v_mfma_f32_16x16x32_bf16 v[12:15], v[156:159], v[204:207], v[12:15]
	v_mfma_f32_16x16x32_bf16 v[60:63], v[152:155], v[184:187], v[60:63]
	v_mfma_f32_16x16x32_bf16 v[56:59], v[160:163], v[184:187], v[56:59]
	v_mfma_f32_16x16x32_bf16 v[52:55], v[152:155], v[192:195], v[52:55]
	v_mfma_f32_16x16x32_bf16 v[44:47], v[160:163], v[192:195], v[44:47]
	v_mfma_f32_16x16x32_bf16 v[36:39], v[152:155], v[200:203], v[36:39]
	v_mfma_f32_16x16x32_bf16 v[28:31], v[160:163], v[200:203], v[28:31]
	v_mfma_f32_16x16x32_bf16 v[20:23], v[152:155], v[210:213], v[20:23]
	v_mfma_f32_16x16x32_bf16 v[12:15], v[160:163], v[210:213], v[12:15]
	s_nop 0
	s_nop 0
	v_mfma_f32_16x16x32_bf16 v[48:51], v[164:167], v[180:183], v[48:51]
	v_mfma_f32_16x16x32_bf16 v[40:43], v[172:175], v[180:183], v[40:43]
	v_mfma_f32_16x16x32_bf16 v[32:35], v[164:167], v[188:191], v[32:35]
	v_mfma_f32_16x16x32_bf16 v[24:27], v[172:175], v[188:191], v[24:27]
	v_mfma_f32_16x16x32_bf16 v[16:19], v[164:167], v[196:199], v[16:19]
	v_mfma_f32_16x16x32_bf16 v[8:11], v[172:175], v[196:199], v[8:11]
	v_mfma_f32_16x16x32_bf16 v[4:7], v[164:167], v[204:207], v[4:7]
	v_mfma_f32_16x16x32_bf16 v[0:3], v[172:175], v[204:207], v[0:3]
	v_mfma_f32_16x16x32_bf16 v[48:51], v[168:171], v[184:187], v[48:51]
	v_mfma_f32_16x16x32_bf16 v[40:43], v[176:179], v[184:187], v[40:43]
	v_mfma_f32_16x16x32_bf16 v[32:35], v[168:171], v[192:195], v[32:35]
	v_mfma_f32_16x16x32_bf16 v[24:27], v[176:179], v[192:195], v[24:27]
	v_mfma_f32_16x16x32_bf16 v[16:19], v[168:171], v[200:203], v[16:19]
	v_mfma_f32_16x16x32_bf16 v[8:11], v[176:179], v[200:203], v[8:11]
	v_mfma_f32_16x16x32_bf16 v[4:7], v[168:171], v[210:213], v[4:7]
	v_mfma_f32_16x16x32_bf16 v[0:3], v[176:179], v[210:213], v[0:3]
	s_setprio 0
	s_barrier
	s_movk_i32 s38, 0x100
	s_andn2_b64 vcc, exec, s[8:9]
	s_mov_b64 s[4:5], -1
	s_mov_b64 s[8:9], 0
	s_cbranch_vccz .LBB0_417
	s_and_b64 vcc, exec, s[16:17]
	s_cbranch_vccz .LBB0_420
	s_barrier

; #define PG8_STAGE(bufoff, gbase, voff) do { _Pragma("unroll") for (int _i = 0; _i < 2; ++_i) \
;         __builtin_amdgcn_global_load_lds((const unsigned*)((const char*)(gbase) + (voff)[_i]), (LAS unsigned*)(lds + (bufoff) + ldsw + _i * 8192), 16, 0, 0); } while (0)
; #define PG8_LDA(dst, b, h) do { _Pragma("unroll") for (int m = 0; m < 4; ++m) _Pragma("unroll") for (int k = 0; k < 2; ++k) dst[m][k] = *(const LAS bf16x8*)(lds + PG8_SA(b, h) + aoff + m * 2048 + k * 1024); } while (0)
; #define PG8_LDB(dst, b, h) do { _Pragma("unroll") for (int n = 0; n < 2; ++n) _Pragma("unroll") for (int k = 0; k < 2; ++k) dst[n][k] = *(const LAS bf16x8*)(lds + PG8_SB(b, h) + boff + n * 2048 + k * 1024); } while (0)
; #define PG8_MMA(ai, bj, At, Bt) do { __builtin_amdgcn_s_setprio(1); _Pragma("unroll") for (int m = 0; m < 4; ++m) _Pragma("unroll") for (int n = 0; n < 2; ++n) _Pragma("unroll") for (int k = 0; k < 2; ++k) \
;         acc[ai][bj][m][n] = __builtin_amdgcn_mfma_f32_16x16x32_bf16(Bt[n][k], At[m][k], acc[ai][bj][m][n], 0, 0, 0); __builtin_amdgcn_s_setprio(0); } while (0)
; #define PG8_WAIT_V(n) asm volatile("s_waitcnt vmcnt(" #n ")" ::: "memory")
; #define PG8_WAIT_L(n) asm volatile("s_waitcnt lgkmcnt(" #n ")" ::: "memory")
; #define PG8_BAR __builtin_amdgcn_s_barrier()
; #define PG8_SCHED __builtin_amdgcn_sched_barrier(0)
; template <class Epi, class Sched>
; __device__ __forceinline__ void gemm_phase(LAS unsigned char* lds, const Gemm g, const Sched& S, const Epi& E, const int wave_s) {
;     ...
;             PG8_LDB(B0, 0, 0); PG8_LDB(B1, 0, 1); PG8_SCHED; PG8_LDA(At, 0, 0); PG8_STAGE(PG8_SA(1, 1), a1 + hstepA, voffA);
;             PG8_WAIT_V(8); PG8_WAIT_L(0); PG8_BAR; PG8_MMA(0, 0, At, B0); PG8_MMA(0, 1, At, B1); PG8_BAR; PG8_SCHED;
;             PG8_LDA(At, 0, 1); PG8_STAGE(PG8_SB(0, 0), b2, voffB); PG8_STAGE(PG8_SB(0, 1), b2 + hstepB, voffB); PG8_STAGE(PG8_SA(0, 0), a2, voffA);
;             PG8_WAIT_V(8); PG8_WAIT_L(0); PG8_BAR; PG8_MMA(1, 0, At, B0); PG8_MMA(1, 1, At, B1); PG8_BAR; PG8_SCHED;
.LBB0_860:
	ds_read_b128 v[100:103], v212
	ds_read_b128 v[108:111], v212 offset:1024
	ds_read_b128 v[136:139], v212 offset:2048
	ds_read_b128 v[140:143], v212 offset:3072
	ds_read_b128 v[144:147], v213
	ds_read_b128 v[148:151], v213 offset:1024
	ds_read_b128 v[152:155], v213 offset:2048
	ds_read_b128 v[156:159], v213 offset:3072
	s_add_u32 s4, s40, 0xfffc0080
	s_addc_u32 s5, s41, -1
	s_cmp_eq_u32 s54, 12
	s_cselect_b32 s43, s9, s5
	s_cselect_b32 s42, s27, s4
	s_cselect_b32 s5, s29, s53
	s_cselect_b32 s4, s31, s39
	v_lshl_add_u64 v[206:207], s[40:41], 0, v[178:179]
	s_add_i32 m0, s3, 0xc000
	ds_read_b128 v[160:163], v214
	ds_read_b128 v[164:167], v214 offset:1024
	ds_read_b128 v[186:189], v214 offset:2048
	ds_read_b128 v[190:193], v214 offset:3072
	ds_read_b128 v[194:197], v214 offset:4096
	ds_read_b128 v[198:201], v214 offset:5120
	ds_read_b128 v[202:205], v214 offset:6144
	ds_read_b128 v[216:219], v214 offset:7168
	global_load_lds_dwordx4 v[206:207], off
	v_lshl_add_u64 v[206:207], s[40:41], 0, v[180:181]
	s_add_i32 m0, s3, 0xe000
	s_nop 0
	global_load_lds_dwordx4 v[206:207], off
	s_waitcnt vmcnt(8) lgkmcnt(0)
	s_barrier
	s_setprio 1
	v_mfma_f32_16x16x32_bf16 v[132:135], v[100:103], v[160:163], v[132:135]
	v_mfma_f32_16x16x32_bf16 v[128:131], v[136:139], v[160:163], v[128:131]
	v_mfma_f32_16x16x32_bf16 v[124:127], v[100:103], v[186:189], v[124:127]
	v_mfma_f32_16x16x32_bf16 v[120:123], v[136:139], v[186:189], v[120:123]
	v_mfma_f32_16x16x32_bf16 v[116:119], v[100:103], v[194:197], v[116:119]
	v_mfma_f32_16x16x32_bf16 v[112:115], v[136:139], v[194:197], v[112:115]
	v_mfma_f32_16x16x32_bf16 v[104:107], v[100:103], v[202:205], v[104:107]
	v_mfma_f32_16x16x32_bf16 v[96:99], v[136:139], v[202:205], v[96:99]
	v_mfma_f32_16x16x32_bf16 v[132:135], v[108:111], v[164:167], v[132:135]
	v_mfma_f32_16x16x32_bf16 v[128:131], v[140:143], v[164:167], v[128:131]
	v_mfma_f32_16x16x32_bf16 v[124:127], v[108:111], v[190:193], v[124:127]
	v_mfma_f32_16x16x32_bf16 v[120:123], v[140:143], v[190:193], v[120:123]
	v_mfma_f32_16x16x32_bf16 v[116:119], v[108:111], v[198:201], v[116:119]
	v_mfma_f32_16x16x32_bf16 v[112:115], v[140:143], v[198:201], v[112:115]
	v_mfma_f32_16x16x32_bf16 v[104:107], v[108:111], v[216:219], v[104:107]
	v_mfma_f32_16x16x32_bf16 v[96:99], v[140:143], v[216:219], v[96:99]
	s_nop 0
	s_nop 0
	v_mfma_f32_16x16x32_bf16 v[60:63], v[144:147], v[160:163], v[60:63]
	v_mfma_f32_16x16x32_bf16 v[56:59], v[152:155], v[160:163], v[56:59]
	v_mfma_f32_16x16x32_bf16 v[52:55], v[144:147], v[186:189], v[52:55]
	v_mfma_f32_16x16x32_bf16 v[48:51], v[152:155], v[186:189], v[48:51]
	v_mfma_f32_16x16x32_bf16 v[44:47], v[144:147], v[194:197], v[44:47]
	v_mfma_f32_16x16x32_bf16 v[40:43], v[152:155], v[194:197], v[40:43]
	v_mfma_f32_16x16x32_bf16 v[36:39], v[144:147], v[202:205], v[36:39]
	v_mfma_f32_16x16x32_bf16 v[32:35], v[152:155], v[202:205], v[32:35]
	v_mfma_f32_16x16x32_bf16 v[60:63], v[148:151], v[164:167], v[60:63]
	v_mfma_f32_16x16x32_bf16 v[56:59], v[156:159], v[164:167], v[56:59]
	v_mfma_f32_16x16x32_bf16 v[52:55], v[148:151], v[190:193], v[52:55]
	v_mfma_f32_16x16x32_bf16 v[48:51], v[156:159], v[190:193], v[48:51]
	v_mfma_f32_16x16x32_bf16 v[44:47], v[148:151], v[198:201], v[44:47]
	v_mfma_f32_16x16x32_bf16 v[40:43], v[156:159], v[198:201], v[40:43]
	v_mfma_f32_16x16x32_bf16 v[36:39], v[148:151], v[216:219], v[36:39]
	v_mfma_f32_16x16x32_bf16 v[32:35], v[156:159], v[216:219], v[32:35]
	s_setprio 0
	s_barrier
	s_add_i32 s55, s50, s81
	v_lshl_add_u64 v[206:207], s[4:5], 0, v[170:171]
	s_mov_b32 m0, s55
	ds_read_b128 v[160:163], v214 offset:16384
	ds_read_b128 v[164:167], v214 offset:17408
	ds_read_b128 v[186:189], v214 offset:18432
	ds_read_b128 v[190:193], v214 offset:19456
	ds_read_b128 v[194:197], v214 offset:20480
	ds_read_b128 v[198:201], v214 offset:21504
	ds_read_b128 v[202:205], v214 offset:22528
	ds_read_b128 v[216:219], v214 offset:23552
	global_load_lds_dwordx4 v[206:207], off
	s_add_i32 m0, s55, 0x2000
	s_add_u32 s56, s4, 0x40000
	v_lshl_add_u64 v[220:221], s[4:5], 0, v[174:175]
	s_addc_u32 s57, s5, 0
	s_add_i32 s55, s51, s81
	global_load_lds_dwordx4 v[220:221], off
	v_lshl_add_u64 v[222:223], s[56:57], 0, v[170:171]
	s_mov_b32 m0, s55
	v_lshl_add_u64 v[224:225], s[42:43], 0, v[172:173]
	global_load_lds_dwordx4 v[222:223], off
	v_lshl_add_u64 v[222:223], s[56:57], 0, v[174:175]
	s_add_i32 m0, s55, 0x2000
	s_nop 0
	global_load_lds_dwordx4 v[222:223], off
	v_lshl_add_u64 v[222:223], s[42:43], 0, v[168:169]
	s_mov_b32 m0, s3
	s_nop 0
	global_load_lds_dwordx4 v[222:223], off
	s_mov_b32 m0, s33
	s_nop 0
	global_load_lds_dwordx4 v[224:225], off
	s_waitcnt vmcnt(8) lgkmcnt(0)
	s_barrier
; #define PG8_STAGE(bufoff, gbase, voff) do { _Pragma("unroll") for (int _i = 0; _i < 2; ++_i) \
;         __builtin_amdgcn_global_load_lds((const unsigned*)((const char*)(gbase) + (voff)[_i]), (LAS unsigned*)(lds + (bufoff) + ldsw + _i * 8192), 16, 0, 0); } while (0)
; #define PG8_LDA(dst, b, h) do { _Pragma("unroll") for (int m = 0; m < 4; ++m) _Pragma("unroll") for (int k = 0; k < 2; ++k) dst[m][k] = *(const LAS bf16x8*)(lds + PG8_SA(b, h) + aoff + m * 2048 + k * 1024); } while (0)
; #define PG8_LDB(dst, b, h) do { _Pragma("unroll") for (int n = 0; n < 2; ++n) _Pragma("unroll") for (int k = 0; k < 2; ++k) dst[n][k] = *(const LAS bf16x8*)(lds + PG8_SB(b, h) + boff + n * 2048 + k * 1024); } while (0)
; #define PG8_MMA(ai, bj, At, Bt) do { __builtin_amdgcn_s_setprio(1); _Pragma("unroll") for (int m = 0; m < 4; ++m) _Pragma("unroll") for (int n = 0; n < 2; ++n) _Pragma("unroll") for (int k = 0; k < 2; ++k) \
;         acc[ai][bj][m][n] = __builtin_amdgcn_mfma_f32_16x16x32_bf16(Bt[n][k], At[m][k], acc[ai][bj][m][n], 0, 0, 0); __builtin_amdgcn_s_setprio(0); } while (0)
; #define PG8_WAIT_V(n) asm volatile("s_waitcnt vmcnt(" #n ")" ::: "memory")
; #define PG8_WAIT_L(n) asm volatile("s_waitcnt lgkmcnt(" #n ")" ::: "memory")
; #define PG8_BAR __builtin_amdgcn_s_barrier()
; #define PG8_SCHED __builtin_amdgcn_sched_barrier(0)
; template <class Epi, class Sched>
; __device__ __forceinline__ void gemm_phase(LAS unsigned char* lds, const Gemm g, const Sched& S, const Epi& E, const int wave_s) {
;     ...
;             PG8_WAIT_V(8); PG8_WAIT_L(0); PG8_BAR; PG8_MMA(1, 0, At, B0); PG8_MMA(1, 1, At, B1); PG8_BAR; PG8_SCHED;
;             PG8_LDB(B0, 1, 0); PG8_LDB(B1, 1, 1); PG8_SCHED; PG8_LDA(At, 1, 0); PG8_STAGE(PG8_SA(0, 1), a2 + hstepA, voffA);
;             PG8_WAIT_V(8); PG8_WAIT_L(0); PG8_BAR; PG8_MMA(0, 0, At, B0); PG8_MMA(0, 1, At, B1); PG8_BAR; PG8_SCHED;
	s_setprio 1
	v_mfma_f32_16x16x32_bf16 v[92:95], v[100:103], v[160:163], v[92:95]
	v_mfma_f32_16x16x32_bf16 v[88:91], v[136:139], v[160:163], v[88:91]
	v_mfma_f32_16x16x32_bf16 v[84:87], v[100:103], v[186:189], v[84:87]
	v_mfma_f32_16x16x32_bf16 v[80:83], v[136:139], v[186:189], v[80:83]
	v_mfma_f32_16x16x32_bf16 v[76:79], v[100:103], v[194:197], v[76:79]
	v_mfma_f32_16x16x32_bf16 v[72:75], v[136:139], v[194:197], v[72:75]
	v_mfma_f32_16x16x32_bf16 v[68:71], v[100:103], v[202:205], v[68:71]
	v_mfma_f32_16x16x32_bf16 v[64:67], v[136:139], v[202:205], v[64:67]
	v_mfma_f32_16x16x32_bf16 v[92:95], v[108:111], v[164:167], v[92:95]
	v_mfma_f32_16x16x32_bf16 v[88:91], v[140:143], v[164:167], v[88:91]
	v_mfma_f32_16x16x32_bf16 v[84:87], v[108:111], v[190:193], v[84:87]
	v_mfma_f32_16x16x32_bf16 v[80:83], v[140:143], v[190:193], v[80:83]
	v_mfma_f32_16x16x32_bf16 v[76:79], v[108:111], v[198:201], v[76:79]
	v_mfma_f32_16x16x32_bf16 v[72:75], v[140:143], v[198:201], v[72:75]
	v_mfma_f32_16x16x32_bf16 v[68:71], v[108:111], v[216:219], v[68:71]
	v_mfma_f32_16x16x32_bf16 v[64:67], v[140:143], v[216:219], v[64:67]
	s_nop 0
	s_nop 0
	v_mfma_f32_16x16x32_bf16 v[28:31], v[144:147], v[160:163], v[28:31]
	v_mfma_f32_16x16x32_bf16 v[24:27], v[152:155], v[160:163], v[24:27]
	v_mfma_f32_16x16x32_bf16 v[20:23], v[144:147], v[186:189], v[20:23]
	v_mfma_f32_16x16x32_bf16 v[16:19], v[152:155], v[186:189], v[16:19]
	v_mfma_f32_16x16x32_bf16 v[12:15], v[144:147], v[194:197], v[12:15]
	v_mfma_f32_16x16x32_bf16 v[8:11], v[152:155], v[194:197], v[8:11]
	v_mfma_f32_16x16x32_bf16 v[4:7], v[144:147], v[202:205], v[4:7]
	v_mfma_f32_16x16x32_bf16 v[0:3], v[152:155], v[202:205], v[0:3]
	v_mfma_f32_16x16x32_bf16 v[28:31], v[148:151], v[164:167], v[28:31]
	v_mfma_f32_16x16x32_bf16 v[24:27], v[156:159], v[164:167], v[24:27]
	v_mfma_f32_16x16x32_bf16 v[20:23], v[148:151], v[190:193], v[20:23]
	v_mfma_f32_16x16x32_bf16 v[16:19], v[156:159], v[190:193], v[16:19]
	v_mfma_f32_16x16x32_bf16 v[12:15], v[148:151], v[198:201], v[12:15]
	v_mfma_f32_16x16x32_bf16 v[8:11], v[156:159], v[198:201], v[8:11]
	v_mfma_f32_16x16x32_bf16 v[4:7], v[148:151], v[216:219], v[4:7]
	v_mfma_f32_16x16x32_bf16 v[0:3], v[156:159], v[216:219], v[0:3]
	s_setprio 0
	s_barrier
	s_add_i32 s55, 0, 0x18000
	s_add_i32 s56, 0, 0x1c000
	v_add_u32_e32 v140, s55, v210
	v_add_u32_e32 v156, s56, v210
	ds_read_b128 v[100:103], v140
	ds_read_b128 v[108:111], v140 offset:1024
	ds_read_b128 v[136:139], v140 offset:2048
	ds_read_b128 v[140:143], v140 offset:3072
	ds_read_b128 v[144:147], v156
	ds_read_b128 v[148:151], v156 offset:1024
	ds_read_b128 v[152:155], v156 offset:2048
	ds_read_b128 v[156:159], v156 offset:3072
	s_add_u32 s42, s42, 0x40000
	s_addc_u32 s43, s43, 0
	s_mov_b32 m0, s44
	v_lshl_add_u64 v[226:227], s[42:43], 0, v[168:169]
	ds_read_b128 v[160:163], v214 offset:32768
	ds_read_b128 v[164:167], v214 offset:33792
	ds_read_b128 v[186:189], v214 offset:34816
	ds_read_b128 v[190:193], v214 offset:35840
	ds_read_b128 v[194:197], v214 offset:36864
	ds_read_b128 v[198:201], v214 offset:37888
	ds_read_b128 v[202:205], v214 offset:38912
	ds_read_b128 v[216:219], v214 offset:39936
	global_load_lds_dwordx4 v[226:227], off
	v_lshl_add_u64 v[226:227], s[42:43], 0, v[172:173]
	s_mov_b32 m0, s45
	s_nop 0
	global_load_lds_dwordx4 v[226:227], off
	s_waitcnt vmcnt(8) lgkmcnt(0)
	s_barrier
	s_setprio 1
	v_mfma_f32_16x16x32_bf16 v[132:135], v[100:103], v[160:163], v[132:135]
	v_mfma_f32_16x16x32_bf16 v[128:131], v[136:139], v[160:163], v[128:131]
	v_mfma_f32_16x16x32_bf16 v[124:127], v[100:103], v[186:189], v[124:127]
	v_mfma_f32_16x16x32_bf16 v[120:123], v[136:139], v[186:189], v[120:123]
	v_mfma_f32_16x16x32_bf16 v[116:119], v[100:103], v[194:197], v[116:119]
	v_mfma_f32_16x16x32_bf16 v[112:115], v[136:139], v[194:197], v[112:115]
	v_mfma_f32_16x16x32_bf16 v[104:107], v[100:103], v[202:205], v[104:107]
	v_mfma_f32_16x16x32_bf16 v[96:99], v[136:139], v[202:205], v[96:99]
	v_mfma_f32_16x16x32_bf16 v[132:135], v[108:111], v[164:167], v[132:135]
	v_mfma_f32_16x16x32_bf16 v[128:131], v[140:143], v[164:167], v[128:131]
	v_mfma_f32_16x16x32_bf16 v[124:127], v[108:111], v[190:193], v[124:127]
	v_mfma_f32_16x16x32_bf16 v[120:123], v[140:143], v[190:193], v[120:123]
	v_mfma_f32_16x16x32_bf16 v[116:119], v[108:111], v[198:201], v[116:119]
	v_mfma_f32_16x16x32_bf16 v[112:115], v[140:143], v[198:201], v[112:115]
	v_mfma_f32_16x16x32_bf16 v[104:107], v[108:111], v[216:219], v[104:107]
	v_mfma_f32_16x16x32_bf16 v[96:99], v[140:143], v[216:219], v[96:99]
	s_nop 0
	s_nop 0
	v_mfma_f32_16x16x32_bf16 v[60:63], v[144:147], v[160:163], v[60:63]
	v_mfma_f32_16x16x32_bf16 v[56:59], v[152:155], v[160:163], v[56:59]
	v_mfma_f32_16x16x32_bf16 v[52:55], v[144:147], v[186:189], v[52:55]
	v_mfma_f32_16x16x32_bf16 v[48:51], v[152:155], v[186:189], v[48:51]
	v_mfma_f32_16x16x32_bf16 v[44:47], v[144:147], v[194:197], v[44:47]
	v_mfma_f32_16x16x32_bf16 v[40:43], v[152:155], v[194:197], v[40:43]
	v_mfma_f32_16x16x32_bf16 v[36:39], v[144:147], v[202:205], v[36:39]
	v_mfma_f32_16x16x32_bf16 v[32:35], v[152:155], v[202:205], v[32:35]
	v_mfma_f32_16x16x32_bf16 v[60:63], v[148:151], v[164:167], v[60:63]
	v_mfma_f32_16x16x32_bf16 v[56:59], v[156:159], v[164:167], v[56:59]
	v_mfma_f32_16x16x32_bf16 v[52:55], v[148:151], v[190:193], v[52:55]
	v_mfma_f32_16x16x32_bf16 v[48:51], v[156:159], v[190:193], v[48:51]
	v_mfma_f32_16x16x32_bf16 v[44:47], v[148:151], v[198:201], v[44:47]
	v_mfma_f32_16x16x32_bf16 v[40:43], v[156:159], v[198:201], v[40:43]
	v_mfma_f32_16x16x32_bf16 v[36:39], v[148:151], v[216:219], v[36:39]
	v_mfma_f32_16x16x32_bf16 v[32:35], v[156:159], v[216:219], v[32:35]
	s_setprio 0
	s_barrier
; #define PG8_STAGE(bufoff, gbase, voff) do { _Pragma("unroll") for (int _i = 0; _i < 2; ++_i) \
;         __builtin_amdgcn_global_load_lds((const unsigned*)((const char*)(gbase) + (voff)[_i]), (LAS unsigned*)(lds + (bufoff) + ldsw + _i * 8192), 16, 0, 0); } while (0)
; #define PG8_LDA(dst, b, h) do { _Pragma("unroll") for (int m = 0; m < 4; ++m) _Pragma("unroll") for (int k = 0; k < 2; ++k) dst[m][k] = *(const LAS bf16x8*)(lds + PG8_SA(b, h) + aoff + m * 2048 + k * 1024); } while (0)
; #define PG8_MMA(ai, bj, At, Bt) do { __builtin_amdgcn_s_setprio(1); _Pragma("unroll") for (int m = 0; m < 4; ++m) _Pragma("unroll") for (int n = 0; n < 2; ++n) _Pragma("unroll") for (int k = 0; k < 2; ++k) \
;         acc[ai][bj][m][n] = __builtin_amdgcn_mfma_f32_16x16x32_bf16(Bt[n][k], At[m][k], acc[ai][bj][m][n], 0, 0, 0); __builtin_amdgcn_s_setprio(0); } while (0)
; #define PG8_WAIT_V(n) asm volatile("s_waitcnt vmcnt(" #n ")" ::: "memory")
; #define PG8_WAIT_L(n) asm volatile("s_waitcnt lgkmcnt(" #n ")" ::: "memory")
; #define PG8_BAR __builtin_amdgcn_s_barrier()
; #define PG8_SCHED __builtin_amdgcn_sched_barrier(0)
; template <class Epi, class Sched>
; __device__ __forceinline__ void gemm_phase(LAS unsigned char* lds, const Gemm g, const Sched& S, const Epi& E, const int wave_s) {
;     ...
;             PG8_LDA(At, 1, 1); PG8_STAGE(PG8_SB(1, 0), b3, voffB); PG8_STAGE(PG8_SB(1, 1), b3 + hstepB, voffB); PG8_STAGE(PG8_SA(1, 0), a3, voffA);
;             PG8_WAIT_V(8); PG8_WAIT_L(0); PG8_BAR; PG8_MMA(1, 0, At, B0); PG8_MMA(1, 1, At, B1); PG8_BAR; PG8_SCHED;
;         }
;         if (wr == 0) PG8_BAR;
	s_add_i32 s42, s55, s81
	v_lshl_add_u64 v[206:207], v[206:207], 0, s[22:23]
	s_mov_b32 m0, s42
	ds_read_b128 v[160:163], v214 offset:49152
	ds_read_b128 v[164:167], v214 offset:50176
	ds_read_b128 v[186:189], v214 offset:51200
	ds_read_b128 v[190:193], v214 offset:52224
	ds_read_b128 v[194:197], v214 offset:53248
	ds_read_b128 v[198:201], v214 offset:54272
	ds_read_b128 v[202:205], v214 offset:55296
	ds_read_b128 v[216:219], v214 offset:56320
	global_load_lds_dwordx4 v[206:207], off
	s_add_i32 m0, s42, 0x2000
	s_add_u32 s4, s4, 0x40080
	v_lshl_add_u64 v[206:207], v[220:221], 0, s[22:23]
	s_addc_u32 s5, s5, 0
	s_add_i32 s42, s56, s81
	global_load_lds_dwordx4 v[206:207], off
	v_lshl_add_u64 v[206:207], s[4:5], 0, v[170:171]
	s_mov_b32 m0, s42
	s_nop 0
	global_load_lds_dwordx4 v[206:207], off
	v_lshl_add_u64 v[206:207], s[4:5], 0, v[174:175]
	s_add_i32 m0, s42, 0x2000
	s_nop 0
	global_load_lds_dwordx4 v[206:207], off
	v_lshl_add_u64 v[206:207], v[222:223], 0, s[22:23]
	s_mov_b32 m0, s47
	s_nop 0
	global_load_lds_dwordx4 v[206:207], off
	v_lshl_add_u64 v[206:207], v[224:225], 0, s[22:23]
	s_mov_b32 m0, s48
	s_nop 0
	global_load_lds_dwordx4 v[206:207], off
	s_waitcnt vmcnt(8) lgkmcnt(0)
	s_barrier
	s_setprio 1
	v_mfma_f32_16x16x32_bf16 v[92:95], v[100:103], v[160:163], v[92:95]
	v_mfma_f32_16x16x32_bf16 v[88:91], v[136:139], v[160:163], v[88:91]
	v_mfma_f32_16x16x32_bf16 v[84:87], v[100:103], v[186:189], v[84:87]
	v_mfma_f32_16x16x32_bf16 v[80:83], v[136:139], v[186:189], v[80:83]
	v_mfma_f32_16x16x32_bf16 v[76:79], v[100:103], v[194:197], v[76:79]
	v_mfma_f32_16x16x32_bf16 v[72:75], v[136:139], v[194:197], v[72:75]
	v_mfma_f32_16x16x32_bf16 v[68:71], v[100:103], v[202:205], v[68:71]
	v_mfma_f32_16x16x32_bf16 v[64:67], v[136:139], v[202:205], v[64:67]
	v_mfma_f32_16x16x32_bf16 v[92:95], v[108:111], v[164:167], v[92:95]
	v_mfma_f32_16x16x32_bf16 v[88:91], v[140:143], v[164:167], v[88:91]
	v_mfma_f32_16x16x32_bf16 v[84:87], v[108:111], v[190:193], v[84:87]
	v_mfma_f32_16x16x32_bf16 v[80:83], v[140:143], v[190:193], v[80:83]
	v_mfma_f32_16x16x32_bf16 v[76:79], v[108:111], v[198:201], v[76:79]
	v_mfma_f32_16x16x32_bf16 v[72:75], v[140:143], v[198:201], v[72:75]
	v_mfma_f32_16x16x32_bf16 v[68:71], v[108:111], v[216:219], v[68:71]
	v_mfma_f32_16x16x32_bf16 v[64:67], v[140:143], v[216:219], v[64:67]
	s_nop 0
	s_nop 0
	v_mfma_f32_16x16x32_bf16 v[28:31], v[144:147], v[160:163], v[28:31]
	v_mfma_f32_16x16x32_bf16 v[24:27], v[152:155], v[160:163], v[24:27]
	v_mfma_f32_16x16x32_bf16 v[20:23], v[144:147], v[186:189], v[20:23]
	v_mfma_f32_16x16x32_bf16 v[16:19], v[152:155], v[186:189], v[16:19]
	v_mfma_f32_16x16x32_bf16 v[12:15], v[144:147], v[194:197], v[12:15]
	v_mfma_f32_16x16x32_bf16 v[8:11], v[152:155], v[194:197], v[8:11]
	v_mfma_f32_16x16x32_bf16 v[4:7], v[144:147], v[202:205], v[4:7]
	v_mfma_f32_16x16x32_bf16 v[0:3], v[152:155], v[202:205], v[0:3]
	v_mfma_f32_16x16x32_bf16 v[28:31], v[148:151], v[164:167], v[28:31]
	v_mfma_f32_16x16x32_bf16 v[24:27], v[156:159], v[164:167], v[24:27]
	v_mfma_f32_16x16x32_bf16 v[20:23], v[148:151], v[190:193], v[20:23]
	v_mfma_f32_16x16x32_bf16 v[16:19], v[156:159], v[190:193], v[16:19]
	v_mfma_f32_16x16x32_bf16 v[12:15], v[148:151], v[198:201], v[12:15]
	v_mfma_f32_16x16x32_bf16 v[8:11], v[156:159], v[198:201], v[8:11]
	v_mfma_f32_16x16x32_bf16 v[4:7], v[148:151], v[216:219], v[4:7]
	v_mfma_f32_16x16x32_bf16 v[0:3], v[156:159], v[216:219], v[0:3]
	s_setprio 0
	s_barrier
	s_add_i32 s54, s54, 2
	s_add_u32 s40, s40, 0x100
	s_addc_u32 s41, s41, 0
	s_add_u32 s39, s39, 0x100
	s_addc_u32 s53, s53, 0
	s_cmp_gt_u32 s54, 13
	s_cbranch_scc0 .LBB0_860
	s_and_b64 vcc, exec, s[24:25]
	s_cbranch_vccz .LBB0_863
	s_barrier

; #define PG8_STAGE(bufoff, gbase, voff) do { _Pragma("unroll") for (int _i = 0; _i < 2; ++_i) \
;         __builtin_amdgcn_global_load_lds((const unsigned*)((const char*)(gbase) + (voff)[_i]), (LAS unsigned*)(lds + (bufoff) + ldsw + _i * 8192), 16, 0, 0); } while (0)
; #define PG8_LDA(dst, b, h) do { _Pragma("unroll") for (int m = 0; m < 4; ++m) _Pragma("unroll") for (int k = 0; k < 2; ++k) dst[m][k] = *(const LAS bf16x8*)(lds + PG8_SA(b, h) + aoff + m * 2048 + k * 1024); } while (0)
; #define PG8_LDB(dst, b, h) do { _Pragma("unroll") for (int n = 0; n < 2; ++n) _Pragma("unroll") for (int k = 0; k < 2; ++k) dst[n][k] = *(const LAS bf16x8*)(lds + PG8_SB(b, h) + boff + n * 2048 + k * 1024); } while (0)
; #define PG8_MMA(ai, bj, At, Bt) do { __builtin_amdgcn_s_setprio(1); _Pragma("unroll") for (int m = 0; m < 4; ++m) _Pragma("unroll") for (int n = 0; n < 2; ++n) _Pragma("unroll") for (int k = 0; k < 2; ++k) \
;         acc[ai][bj][m][n] = __builtin_amdgcn_mfma_f32_16x16x32_bf16(Bt[n][k], At[m][k], acc[ai][bj][m][n], 0, 0, 0); __builtin_amdgcn_s_setprio(0); } while (0)
; #define PG8_WAIT_V(n) asm volatile("s_waitcnt vmcnt(" #n ")" ::: "memory")
; #define PG8_WAIT_L(n) asm volatile("s_waitcnt lgkmcnt(" #n ")" ::: "memory")
; #define PG8_BAR __builtin_amdgcn_s_barrier()
; #define PG8_SCHED __builtin_amdgcn_sched_barrier(0)
; template <class Epi, class Sched>
; __device__ __forceinline__ void gemm_phase(LAS unsigned char* lds, const Gemm g, const Sched& S, const Epi& E, const int wave_s) {
;     ...
;             const bool last = (t == nt - 2);
;             const char* a1 = cA + (size_t)(t + 1) * kstep;
;             const char* a2 = last ? nA : cA + (size_t)(t + 2) * kstep; const char* b2 = last ? nB : cB + (size_t)(t + 2) * kstep;
;             const char* a3 = a2 + kstep; const char* b3 = b2 + kstep;
;             PG8_LDB(B0, 0, 0); PG8_LDB(B1, 0, 1); PG8_SCHED; PG8_LDA(At, 0, 0); PG8_STAGE(PG8_SA(1, 1), a1 + hstepA, voffA);
;             PG8_WAIT_V(8); PG8_WAIT_L(0); PG8_BAR; PG8_MMA(0, 0, At, B0); PG8_MMA(0, 1, At, B1); PG8_BAR; PG8_SCHED;
;             PG8_LDA(At, 0, 1); PG8_STAGE(PG8_SB(0, 0), b2, voffB); PG8_STAGE(PG8_SB(0, 1), b2 + hstepB, voffB); PG8_STAGE(PG8_SA(0, 0), a2, voffA);
;             PG8_WAIT_V(8); PG8_WAIT_L(0); PG8_BAR; PG8_MMA(1, 0, At, B0); PG8_MMA(1, 1, At, B1); PG8_BAR; PG8_SCHED;
.LBB0_1024:
	s_add_u32 s48, s64, s46
	s_addc_u32 s49, s65, s47
	s_add_u32 s48, s48, 0x99a5200
	s_addc_u32 s49, s49, 0
	s_add_u32 s73, s70, s46
	s_addc_u32 s74, s71, s47
	s_add_i32 s75, 0, 0x10000
	s_cmpk_eq_i32 s46, 0x700
	s_cselect_b32 s51, s11, s49
	s_cselect_b32 s50, s10, s48
	v_add_u32_e32 v128, s75, v178
	s_cselect_b32 s49, s68, s74
	s_cselect_b32 s48, s69, s73
	s_add_i32 s73, 0, 0x14000
	ds_read_b128 v[170:173], v128
	ds_read_b128 v[182:185], v128 offset:1024
	ds_read_b128 v[186:189], v128 offset:2048
	ds_read_b128 v[190:193], v128 offset:3072
	v_add_u32_e32 v128, s73, v178
	ds_read_b128 v[194:197], v128
	ds_read_b128 v[198:201], v128 offset:1024
	ds_read_b128 v[202:205], v128 offset:2048
	ds_read_b128 v[206:209], v128 offset:3072
	v_lshl_add_u64 v[242:243], v[166:167], 0, s[46:47]
	s_add_i32 m0, s52, 0xc000
	ds_read_b128 v[210:213], v180
	ds_read_b128 v[214:217], v180 offset:1024
	ds_read_b128 v[218:221], v180 offset:2048
	ds_read_b128 v[222:225], v180 offset:3072
	ds_read_b128 v[226:229], v180 offset:4096
	ds_read_b128 v[230:233], v180 offset:5120
	ds_read_b128 v[234:237], v180 offset:6144
	ds_read_b128 v[238:241], v180 offset:7168
	global_load_lds_dwordx4 v[242:243], off
	v_lshl_add_u64 v[242:243], v[168:169], 0, s[46:47]
	s_add_i32 m0, s52, 0xe000
	s_nop 0
	global_load_lds_dwordx4 v[242:243], off
	s_waitcnt vmcnt(8) lgkmcnt(0)
	s_barrier
	s_setprio 1
	v_mfma_f32_16x16x32_bf16 v[124:127], v[170:173], v[210:213], v[124:127]
	v_mfma_f32_16x16x32_bf16 v[120:123], v[186:189], v[210:213], v[120:123]
	v_mfma_f32_16x16x32_bf16 v[116:119], v[170:173], v[218:221], v[116:119]
	v_mfma_f32_16x16x32_bf16 v[112:115], v[186:189], v[218:221], v[112:115]
	v_mfma_f32_16x16x32_bf16 v[108:111], v[170:173], v[226:229], v[108:111]
	v_mfma_f32_16x16x32_bf16 v[100:103], v[186:189], v[226:229], v[100:103]
	v_mfma_f32_16x16x32_bf16 v[92:95], v[170:173], v[234:237], v[92:95]
	v_mfma_f32_16x16x32_bf16 v[84:87], v[186:189], v[234:237], v[84:87]
	v_mfma_f32_16x16x32_bf16 v[124:127], v[182:185], v[214:217], v[124:127]
	v_mfma_f32_16x16x32_bf16 v[120:123], v[190:193], v[214:217], v[120:123]
	v_mfma_f32_16x16x32_bf16 v[116:119], v[182:185], v[222:225], v[116:119]
	v_mfma_f32_16x16x32_bf16 v[112:115], v[190:193], v[222:225], v[112:115]
	v_mfma_f32_16x16x32_bf16 v[108:111], v[182:185], v[230:233], v[108:111]
	v_mfma_f32_16x16x32_bf16 v[100:103], v[190:193], v[230:233], v[100:103]
	v_mfma_f32_16x16x32_bf16 v[92:95], v[182:185], v[238:241], v[92:95]
	v_mfma_f32_16x16x32_bf16 v[84:87], v[190:193], v[238:241], v[84:87]
	s_nop 0
	s_nop 0
	v_mfma_f32_16x16x32_bf16 v[104:107], v[194:197], v[210:213], v[104:107]
	v_mfma_f32_16x16x32_bf16 v[96:99], v[202:205], v[210:213], v[96:99]
	v_mfma_f32_16x16x32_bf16 v[88:91], v[194:197], v[218:221], v[88:91]
	v_mfma_f32_16x16x32_bf16 v[80:83], v[202:205], v[218:221], v[80:83]
	v_mfma_f32_16x16x32_bf16 v[76:79], v[194:197], v[226:229], v[76:79]
	v_mfma_f32_16x16x32_bf16 v[72:75], v[202:205], v[226:229], v[72:75]
	v_mfma_f32_16x16x32_bf16 v[68:71], v[194:197], v[234:237], v[68:71]
	v_mfma_f32_16x16x32_bf16 v[64:67], v[202:205], v[234:237], v[64:67]
	v_mfma_f32_16x16x32_bf16 v[104:107], v[198:201], v[214:217], v[104:107]
	v_mfma_f32_16x16x32_bf16 v[96:99], v[206:209], v[214:217], v[96:99]
	v_mfma_f32_16x16x32_bf16 v[88:91], v[198:201], v[222:225], v[88:91]
	v_mfma_f32_16x16x32_bf16 v[80:83], v[206:209], v[222:225], v[80:83]
	v_mfma_f32_16x16x32_bf16 v[76:79], v[198:201], v[230:233], v[76:79]
	v_mfma_f32_16x16x32_bf16 v[72:75], v[206:209], v[230:233], v[72:75]
	v_mfma_f32_16x16x32_bf16 v[68:71], v[198:201], v[238:241], v[68:71]
	v_mfma_f32_16x16x32_bf16 v[64:67], v[206:209], v[238:241], v[64:67]
	s_setprio 0
	s_barrier
	s_add_i32 s74, s75, s81
	v_lshl_add_u64 v[242:243], s[48:49], 0, v[130:131]
	s_mov_b32 m0, s74
	ds_read_b128 v[210:213], v180 offset:16384
	ds_read_b128 v[214:217], v180 offset:17408
	ds_read_b128 v[218:221], v180 offset:18432
	ds_read_b128 v[222:225], v180 offset:19456
	ds_read_b128 v[226:229], v180 offset:20480
	ds_read_b128 v[230:233], v180 offset:21504
	ds_read_b128 v[234:237], v180 offset:22528
	ds_read_b128 v[238:241], v180 offset:23552
	global_load_lds_dwordx4 v[242:243], off
	s_add_i32 m0, s74, 0x2000
	s_add_u32 s74, s48, 0x40000
	v_lshl_add_u64 v[244:245], s[48:49], 0, v[132:133]
	s_addc_u32 s75, s49, 0
	s_add_i32 s73, s73, s81
	global_load_lds_dwordx4 v[244:245], off
	v_lshl_add_u64 v[246:247], s[74:75], 0, v[130:131]
	s_mov_b32 m0, s73
	v_lshl_add_u64 v[248:249], s[50:51], 0, v[132:133]
	global_load_lds_dwordx4 v[246:247], off
	v_lshl_add_u64 v[246:247], s[74:75], 0, v[132:133]
	s_add_i32 m0, s73, 0x2000
	s_nop 0
	global_load_lds_dwordx4 v[246:247], off
	v_lshl_add_u64 v[246:247], s[50:51], 0, v[130:131]
	s_mov_b32 m0, s52
	s_nop 0
	global_load_lds_dwordx4 v[246:247], off
	s_mov_b32 m0, s57
	s_nop 0
	global_load_lds_dwordx4 v[248:249], off
	s_waitcnt vmcnt(8) lgkmcnt(0)
	s_barrier
; #define PG8_STAGE(bufoff, gbase, voff) do { _Pragma("unroll") for (int _i = 0; _i < 2; ++_i) \
;         __builtin_amdgcn_global_load_lds((const unsigned*)((const char*)(gbase) + (voff)[_i]), (LAS unsigned*)(lds + (bufoff) + ldsw + _i * 8192), 16, 0, 0); } while (0)
; #define PG8_LDA(dst, b, h) do { _Pragma("unroll") for (int m = 0; m < 4; ++m) _Pragma("unroll") for (int k = 0; k < 2; ++k) dst[m][k] = *(const LAS bf16x8*)(lds + PG8_SA(b, h) + aoff + m * 2048 + k * 1024); } while (0)
; #define PG8_LDB(dst, b, h) do { _Pragma("unroll") for (int n = 0; n < 2; ++n) _Pragma("unroll") for (int k = 0; k < 2; ++k) dst[n][k] = *(const LAS bf16x8*)(lds + PG8_SB(b, h) + boff + n * 2048 + k * 1024); } while (0)
; #define PG8_MMA(ai, bj, At, Bt) do { __builtin_amdgcn_s_setprio(1); _Pragma("unroll") for (int m = 0; m < 4; ++m) _Pragma("unroll") for (int n = 0; n < 2; ++n) _Pragma("unroll") for (int k = 0; k < 2; ++k) \
;         acc[ai][bj][m][n] = __builtin_amdgcn_mfma_f32_16x16x32_bf16(Bt[n][k], At[m][k], acc[ai][bj][m][n], 0, 0, 0); __builtin_amdgcn_s_setprio(0); } while (0)
; #define PG8_WAIT_V(n) asm volatile("s_waitcnt vmcnt(" #n ")" ::: "memory")
; #define PG8_WAIT_L(n) asm volatile("s_waitcnt lgkmcnt(" #n ")" ::: "memory")
; #define PG8_BAR __builtin_amdgcn_s_barrier()
; #define PG8_SCHED __builtin_amdgcn_sched_barrier(0)
; template <class Epi, class Sched>
; __device__ __forceinline__ void gemm_phase(LAS unsigned char* lds, const Gemm g, const Sched& S, const Epi& E, const int wave_s) {
;     ...
;             PG8_WAIT_V(8); PG8_WAIT_L(0); PG8_BAR; PG8_MMA(1, 0, At, B0); PG8_MMA(1, 1, At, B1); PG8_BAR; PG8_SCHED;
;             PG8_LDB(B0, 1, 0); PG8_LDB(B1, 1, 1); PG8_SCHED; PG8_LDA(At, 1, 0); PG8_STAGE(PG8_SA(0, 1), a2 + hstepA, voffA);
;             PG8_WAIT_V(8); PG8_WAIT_L(0); PG8_BAR; PG8_MMA(0, 0, At, B0); PG8_MMA(0, 1, At, B1); PG8_BAR; PG8_SCHED;
	s_setprio 1
	v_mfma_f32_16x16x32_bf16 v[60:63], v[170:173], v[210:213], v[60:63]
	v_mfma_f32_16x16x32_bf16 v[56:59], v[186:189], v[210:213], v[56:59]
	v_mfma_f32_16x16x32_bf16 v[52:55], v[170:173], v[218:221], v[52:55]
	v_mfma_f32_16x16x32_bf16 v[48:51], v[186:189], v[218:221], v[48:51]
	v_mfma_f32_16x16x32_bf16 v[44:47], v[170:173], v[226:229], v[44:47]
	v_mfma_f32_16x16x32_bf16 v[36:39], v[186:189], v[226:229], v[36:39]
	v_mfma_f32_16x16x32_bf16 v[28:31], v[170:173], v[234:237], v[28:31]
	v_mfma_f32_16x16x32_bf16 v[20:23], v[186:189], v[234:237], v[20:23]
	v_mfma_f32_16x16x32_bf16 v[60:63], v[182:185], v[214:217], v[60:63]
	v_mfma_f32_16x16x32_bf16 v[56:59], v[190:193], v[214:217], v[56:59]
	v_mfma_f32_16x16x32_bf16 v[52:55], v[182:185], v[222:225], v[52:55]
	v_mfma_f32_16x16x32_bf16 v[48:51], v[190:193], v[222:225], v[48:51]
	v_mfma_f32_16x16x32_bf16 v[44:47], v[182:185], v[230:233], v[44:47]
	v_mfma_f32_16x16x32_bf16 v[36:39], v[190:193], v[230:233], v[36:39]
	v_mfma_f32_16x16x32_bf16 v[28:31], v[182:185], v[238:241], v[28:31]
	v_mfma_f32_16x16x32_bf16 v[20:23], v[190:193], v[238:241], v[20:23]
	s_nop 0
	s_nop 0
	v_mfma_f32_16x16x32_bf16 v[40:43], v[194:197], v[210:213], v[40:43]
	v_mfma_f32_16x16x32_bf16 v[32:35], v[202:205], v[210:213], v[32:35]
	v_mfma_f32_16x16x32_bf16 v[24:27], v[194:197], v[218:221], v[24:27]
	v_mfma_f32_16x16x32_bf16 v[16:19], v[202:205], v[218:221], v[16:19]
	v_mfma_f32_16x16x32_bf16 v[12:15], v[194:197], v[226:229], v[12:15]
	v_mfma_f32_16x16x32_bf16 v[8:11], v[202:205], v[226:229], v[8:11]
	v_mfma_f32_16x16x32_bf16 v[4:7], v[194:197], v[234:237], v[4:7]
	v_mfma_f32_16x16x32_bf16 v[0:3], v[202:205], v[234:237], v[0:3]
	v_mfma_f32_16x16x32_bf16 v[40:43], v[198:201], v[214:217], v[40:43]
	v_mfma_f32_16x16x32_bf16 v[32:35], v[206:209], v[214:217], v[32:35]
	v_mfma_f32_16x16x32_bf16 v[24:27], v[198:201], v[222:225], v[24:27]
	v_mfma_f32_16x16x32_bf16 v[16:19], v[206:209], v[222:225], v[16:19]
	v_mfma_f32_16x16x32_bf16 v[12:15], v[198:201], v[230:233], v[12:15]
	v_mfma_f32_16x16x32_bf16 v[8:11], v[206:209], v[230:233], v[8:11]
	v_mfma_f32_16x16x32_bf16 v[4:7], v[198:201], v[238:241], v[4:7]
	v_mfma_f32_16x16x32_bf16 v[0:3], v[206:209], v[238:241], v[0:3]
	s_setprio 0
	s_barrier
	s_add_i32 s73, 0, 0x18000
	v_add_u32_e32 v128, s73, v178
	s_add_i32 s74, 0, 0x1c000
	ds_read_b128 v[170:173], v128
	ds_read_b128 v[182:185], v128 offset:1024
	ds_read_b128 v[186:189], v128 offset:2048
	ds_read_b128 v[190:193], v128 offset:3072
	v_add_u32_e32 v128, s74, v178
	ds_read_b128 v[194:197], v128
	ds_read_b128 v[198:201], v128 offset:1024
	ds_read_b128 v[202:205], v128 offset:2048
	ds_read_b128 v[206:209], v128 offset:3072
	s_add_u32 s50, s50, 0x40000
	s_addc_u32 s51, s51, 0
	s_mov_b32 m0, s58
	v_lshl_add_u64 v[250:251], s[50:51], 0, v[130:131]
	ds_read_b128 v[210:213], v180 offset:32768
	ds_read_b128 v[214:217], v180 offset:33792
	ds_read_b128 v[218:221], v180 offset:34816
	ds_read_b128 v[222:225], v180 offset:35840
	ds_read_b128 v[226:229], v180 offset:36864
	ds_read_b128 v[230:233], v180 offset:37888
	ds_read_b128 v[234:237], v180 offset:38912
	ds_read_b128 v[238:241], v180 offset:39936
	global_load_lds_dwordx4 v[250:251], off
	v_lshl_add_u64 v[250:251], s[50:51], 0, v[132:133]
	s_mov_b32 m0, s59
	s_nop 0
	global_load_lds_dwordx4 v[250:251], off
	s_waitcnt vmcnt(8) lgkmcnt(0)
	s_barrier
	s_setprio 1
	v_mfma_f32_16x16x32_bf16 v[124:127], v[170:173], v[210:213], v[124:127]
	v_mfma_f32_16x16x32_bf16 v[120:123], v[186:189], v[210:213], v[120:123]
	v_mfma_f32_16x16x32_bf16 v[116:119], v[170:173], v[218:221], v[116:119]
	v_mfma_f32_16x16x32_bf16 v[112:115], v[186:189], v[218:221], v[112:115]
	v_mfma_f32_16x16x32_bf16 v[108:111], v[170:173], v[226:229], v[108:111]
	v_mfma_f32_16x16x32_bf16 v[100:103], v[186:189], v[226:229], v[100:103]
	v_mfma_f32_16x16x32_bf16 v[92:95], v[170:173], v[234:237], v[92:95]
	v_mfma_f32_16x16x32_bf16 v[84:87], v[186:189], v[234:237], v[84:87]
	v_mfma_f32_16x16x32_bf16 v[124:127], v[182:185], v[214:217], v[124:127]
	v_mfma_f32_16x16x32_bf16 v[120:123], v[190:193], v[214:217], v[120:123]
	v_mfma_f32_16x16x32_bf16 v[116:119], v[182:185], v[222:225], v[116:119]
	v_mfma_f32_16x16x32_bf16 v[112:115], v[190:193], v[222:225], v[112:115]
	v_mfma_f32_16x16x32_bf16 v[108:111], v[182:185], v[230:233], v[108:111]
	v_mfma_f32_16x16x32_bf16 v[100:103], v[190:193], v[230:233], v[100:103]
	v_mfma_f32_16x16x32_bf16 v[92:95], v[182:185], v[238:241], v[92:95]
	v_mfma_f32_16x16x32_bf16 v[84:87], v[190:193], v[238:241], v[84:87]
	s_nop 0
	s_nop 0
	v_mfma_f32_16x16x32_bf16 v[104:107], v[194:197], v[210:213], v[104:107]
	v_mfma_f32_16x16x32_bf16 v[96:99], v[202:205], v[210:213], v[96:99]
	v_mfma_f32_16x16x32_bf16 v[88:91], v[194:197], v[218:221], v[88:91]
	v_mfma_f32_16x16x32_bf16 v[80:83], v[202:205], v[218:221], v[80:83]
	v_mfma_f32_16x16x32_bf16 v[76:79], v[194:197], v[226:229], v[76:79]
	v_mfma_f32_16x16x32_bf16 v[72:75], v[202:205], v[226:229], v[72:75]
	v_mfma_f32_16x16x32_bf16 v[68:71], v[194:197], v[234:237], v[68:71]
	v_mfma_f32_16x16x32_bf16 v[64:67], v[202:205], v[234:237], v[64:67]
	v_mfma_f32_16x16x32_bf16 v[104:107], v[198:201], v[214:217], v[104:107]
	v_mfma_f32_16x16x32_bf16 v[96:99], v[206:209], v[214:217], v[96:99]
	v_mfma_f32_16x16x32_bf16 v[88:91], v[198:201], v[222:225], v[88:91]
	v_mfma_f32_16x16x32_bf16 v[80:83], v[206:209], v[222:225], v[80:83]
	v_mfma_f32_16x16x32_bf16 v[76:79], v[198:201], v[230:233], v[76:79]
	v_mfma_f32_16x16x32_bf16 v[72:75], v[206:209], v[230:233], v[72:75]
	v_mfma_f32_16x16x32_bf16 v[68:71], v[198:201], v[238:241], v[68:71]
	v_mfma_f32_16x16x32_bf16 v[64:67], v[206:209], v[238:241], v[64:67]
	s_setprio 0
	s_barrier
; #define PG8_STAGE(bufoff, gbase, voff) do { _Pragma("unroll") for (int _i = 0; _i < 2; ++_i) \
;         __builtin_amdgcn_global_load_lds((const unsigned*)((const char*)(gbase) + (voff)[_i]), (LAS unsigned*)(lds + (bufoff) + ldsw + _i * 8192), 16, 0, 0); } while (0)
; #define PG8_LDA(dst, b, h) do { _Pragma("unroll") for (int m = 0; m < 4; ++m) _Pragma("unroll") for (int k = 0; k < 2; ++k) dst[m][k] = *(const LAS bf16x8*)(lds + PG8_SA(b, h) + aoff + m * 2048 + k * 1024); } while (0)
; #define PG8_MMA(ai, bj, At, Bt) do { __builtin_amdgcn_s_setprio(1); _Pragma("unroll") for (int m = 0; m < 4; ++m) _Pragma("unroll") for (int n = 0; n < 2; ++n) _Pragma("unroll") for (int k = 0; k < 2; ++k) \
;         acc[ai][bj][m][n] = __builtin_amdgcn_mfma_f32_16x16x32_bf16(Bt[n][k], At[m][k], acc[ai][bj][m][n], 0, 0, 0); __builtin_amdgcn_s_setprio(0); } while (0)
; #define PG8_WAIT_V(n) asm volatile("s_waitcnt vmcnt(" #n ")" ::: "memory")
; #define PG8_WAIT_L(n) asm volatile("s_waitcnt lgkmcnt(" #n ")" ::: "memory")
; #define PG8_BAR __builtin_amdgcn_s_barrier()
; #define PG8_SCHED __builtin_amdgcn_sched_barrier(0)
; template <class Epi, class Sched>
; __device__ __forceinline__ void gemm_phase(LAS unsigned char* lds, const Gemm g, const Sched& S, const Epi& E, const int wave_s) {
;     ...
;             PG8_LDA(At, 1, 1); PG8_STAGE(PG8_SB(1, 0), b3, voffB); PG8_STAGE(PG8_SB(1, 1), b3 + hstepB, voffB); PG8_STAGE(PG8_SA(1, 0), a3, voffA);
;             PG8_WAIT_V(8); PG8_WAIT_L(0); PG8_BAR; PG8_MMA(1, 0, At, B0); PG8_MMA(1, 1, At, B1); PG8_BAR; PG8_SCHED;
;         }
	s_add_i32 s50, s73, s81
	v_lshl_add_u64 v[242:243], v[242:243], 0, s[22:23]
	s_mov_b32 m0, s50
	ds_read_b128 v[210:213], v180 offset:49152
	ds_read_b128 v[214:217], v180 offset:50176
	ds_read_b128 v[218:221], v180 offset:51200
	ds_read_b128 v[222:225], v180 offset:52224
	ds_read_b128 v[226:229], v180 offset:53248
	ds_read_b128 v[230:233], v180 offset:54272
	ds_read_b128 v[234:237], v180 offset:55296
	ds_read_b128 v[238:241], v180 offset:56320
	global_load_lds_dwordx4 v[242:243], off
	s_add_i32 m0, s50, 0x2000
	s_add_u32 s48, s48, 0x40080
	v_lshl_add_u64 v[242:243], v[244:245], 0, s[22:23]
	s_addc_u32 s49, s49, 0
	s_add_i32 s50, s74, s81
	global_load_lds_dwordx4 v[242:243], off
	v_lshl_add_u64 v[242:243], s[48:49], 0, v[130:131]
	s_mov_b32 m0, s50
	s_nop 0
	global_load_lds_dwordx4 v[242:243], off
	v_lshl_add_u64 v[242:243], s[48:49], 0, v[132:133]
	s_add_i32 m0, s50, 0x2000
	s_nop 0
	global_load_lds_dwordx4 v[242:243], off
	v_lshl_add_u64 v[242:243], v[246:247], 0, s[22:23]
	s_mov_b32 m0, s20
	s_nop 0
	global_load_lds_dwordx4 v[242:243], off
	v_lshl_add_u64 v[242:243], v[248:249], 0, s[22:23]
	s_mov_b32 m0, s63
	s_nop 0
	global_load_lds_dwordx4 v[242:243], off
	s_waitcnt vmcnt(8) lgkmcnt(0)
	s_barrier
	s_setprio 1
	v_mfma_f32_16x16x32_bf16 v[60:63], v[170:173], v[210:213], v[60:63]
	v_mfma_f32_16x16x32_bf16 v[56:59], v[186:189], v[210:213], v[56:59]
	v_mfma_f32_16x16x32_bf16 v[52:55], v[170:173], v[218:221], v[52:55]
	v_mfma_f32_16x16x32_bf16 v[48:51], v[186:189], v[218:221], v[48:51]
	v_mfma_f32_16x16x32_bf16 v[44:47], v[170:173], v[226:229], v[44:47]
	v_mfma_f32_16x16x32_bf16 v[36:39], v[186:189], v[226:229], v[36:39]
	v_mfma_f32_16x16x32_bf16 v[28:31], v[170:173], v[234:237], v[28:31]
	v_mfma_f32_16x16x32_bf16 v[20:23], v[186:189], v[234:237], v[20:23]
	v_mfma_f32_16x16x32_bf16 v[60:63], v[182:185], v[214:217], v[60:63]
	v_mfma_f32_16x16x32_bf16 v[56:59], v[190:193], v[214:217], v[56:59]
	v_mfma_f32_16x16x32_bf16 v[52:55], v[182:185], v[222:225], v[52:55]
	v_mfma_f32_16x16x32_bf16 v[48:51], v[190:193], v[222:225], v[48:51]
	v_mfma_f32_16x16x32_bf16 v[44:47], v[182:185], v[230:233], v[44:47]
	v_mfma_f32_16x16x32_bf16 v[36:39], v[190:193], v[230:233], v[36:39]
	v_mfma_f32_16x16x32_bf16 v[28:31], v[182:185], v[238:241], v[28:31]
	v_mfma_f32_16x16x32_bf16 v[20:23], v[190:193], v[238:241], v[20:23]
	s_nop 0
	s_nop 0
	v_mfma_f32_16x16x32_bf16 v[40:43], v[194:197], v[210:213], v[40:43]
	v_mfma_f32_16x16x32_bf16 v[32:35], v[202:205], v[210:213], v[32:35]
	v_mfma_f32_16x16x32_bf16 v[24:27], v[194:197], v[218:221], v[24:27]
	v_mfma_f32_16x16x32_bf16 v[16:19], v[202:205], v[218:221], v[16:19]
	v_mfma_f32_16x16x32_bf16 v[12:15], v[194:197], v[226:229], v[12:15]
	v_mfma_f32_16x16x32_bf16 v[8:11], v[202:205], v[226:229], v[8:11]
	v_mfma_f32_16x16x32_bf16 v[4:7], v[194:197], v[234:237], v[4:7]
	v_mfma_f32_16x16x32_bf16 v[0:3], v[202:205], v[234:237], v[0:3]
	v_mfma_f32_16x16x32_bf16 v[40:43], v[198:201], v[214:217], v[40:43]
	v_mfma_f32_16x16x32_bf16 v[32:35], v[206:209], v[214:217], v[32:35]
	v_mfma_f32_16x16x32_bf16 v[24:27], v[198:201], v[222:225], v[24:27]
	v_mfma_f32_16x16x32_bf16 v[16:19], v[206:209], v[222:225], v[16:19]
	v_mfma_f32_16x16x32_bf16 v[12:15], v[198:201], v[230:233], v[12:15]
	v_mfma_f32_16x16x32_bf16 v[8:11], v[206:209], v[230:233], v[8:11]
	v_mfma_f32_16x16x32_bf16 v[4:7], v[198:201], v[238:241], v[4:7]
	v_mfma_f32_16x16x32_bf16 v[0:3], v[206:209], v[238:241], v[0:3]
	s_setprio 0
	s_barrier
	s_add_i32 s72, s72, 2
	s_add_u32 s46, s46, 0x100
	s_addc_u32 s47, s47, 0
	s_cmp_gt_u32 s72, 13
	s_cbranch_scc0 .LBB0_1024
	s_and_b64 vcc, exec, s[12:13]
	s_cbranch_vccz .LBB0_1027
	s_barrier
